# scan: cross-row dot-product reduction via one f32 MFMA (ones x partials) replaces two ds_bpermute butterflies; LDS waits merged
# speedup vs baseline: 1.0894x; 1.0086x over previous
.LBB0_581:
	s_waitcnt vmcnt(63) expcnt(7) lgkmcnt(15)
	s_barrier
	s_and_saveexec_b64 s[12:13], s[0:1]
	s_xor_b64 s[12:13], exec, s[12:13]
	s_cbranch_execz .LBB0_584
	s_mov_b32 s16, 0
	v_mov_b32_e32 v2, 0
	s_mov_b32 s52, 0
	s_mov_b32 s17, 0
	v_mov_b32_e32 v3, 0
	v_mov_b32_e32 v4, 0
	v_mov_b32_e32 v5, 0
	v_mov_b32_e32 v6, 0
	v_mov_b32_e32 v7, 0
	v_mov_b32_e32 v8, 0
	v_mov_b32_e32 v9, 0
	v_mov_b32_e32 v10, 0
	v_mov_b32_e32 v11, 0
	v_mov_b32_e32 v12, 0
	v_mov_b32_e32 v13, 0
	v_mov_b32_e32 v14, 0
	v_mov_b32_e32 v15, 0
	v_mov_b32_e32 v16, 0
	v_mov_b32_e32 v17, 0
	v_mov_b32_e32 v18, 0
	v_mov_b32_e32 v22, 0
	v_mov_b32_e32 v19, 0
	v_mov_b32_e32 v228, 1.0
	s_barrier
.LBB0_583:
	s_and_b32 s48, s16, 1
	v_lshl_add_u32 v21, s48, 9, v135
	ds_read_b128 v[24:27], v21
	ds_read_b128 v[28:31], v21 offset:16
	v_fmac_f32_e32 v18, s52, v22
	s_mul_i32 s52, s48, 0x6000
	v_fmac_f32_e32 v18, s17, v19
	s_add_i32 s17, s52, 0
	v_add3_u32 v19, s17, v157, v72
	v_lshl_add_u32 v21, v73, 2, s17
	ds_read2st64_b32 v[32:33], v19 offset0:80 offset1:81
	ds_read2st64_b32 v[34:35], v21 offset0:16 offset1:17
	ds_read2st64_b32 v[36:37], v21 offset0:32 offset1:33
	ds_read2st64_b32 v[38:39], v21 offset0:48 offset1:49
	ds_read2st64_b32 v[40:41], v21 offset0:64 offset1:65
	s_waitcnt lgkmcnt(6)
	v_mov_b32_e32 v42, v24
	s_waitcnt lgkmcnt(5)
	v_mov_b32_e32 v43, v28
	v_mov_b32_e32 v44, v26
	v_mov_b32_e32 v45, v30
	v_mov_b32_e32 v28, v25
	v_mov_b32_e32 v30, v27
	v_pk_add_f32 v[24:25], v[42:43], v[44:45]
	v_pk_add_f32 v[26:27], v[28:29], v[30:31]
	s_waitcnt lgkmcnt(3)
	v_mul_f32_dpp v42, v34, v17 row_newbcast:0 row_mask:0xf bank_mask:0xf bound_ctrl:1
	v_add_f32_e32 v23, v24, v25
	v_add_f32_e32 v24, v26, v27
	v_mul_f32_dpp v25, v34, v16 row_newbcast:1 row_mask:0xf bank_mask:0xf bound_ctrl:1
	v_mul_f32_dpp v26, v34, v15 row_newbcast:2 row_mask:0xf bank_mask:0xf bound_ctrl:1
	v_mul_f32_dpp v27, v34, v14 row_newbcast:3 row_mask:0xf bank_mask:0xf bound_ctrl:1
	v_fmac_f32_dpp v42, v34, v13 row_newbcast:4 row_mask:0xf bank_mask:0xf bound_ctrl:1
	v_xor_b32_e32 v23, 0x80000000, v23
	v_fmac_f32_dpp v25, v34, v12 row_newbcast:5 row_mask:0xf bank_mask:0xf bound_ctrl:1
	v_fmac_f32_dpp v26, v34, v11 row_newbcast:6 row_mask:0xf bank_mask:0xf bound_ctrl:1
	v_fmac_f32_dpp v27, v34, v10 row_newbcast:7 row_mask:0xf bank_mask:0xf bound_ctrl:1
	v_fmac_f32_dpp v42, v34, v9 row_newbcast:8 row_mask:0xf bank_mask:0xf bound_ctrl:1
	v_xor_b32_e32 v24, 0x80000000, v24
	v_fmac_f32_dpp v25, v34, v8 row_newbcast:9 row_mask:0xf bank_mask:0xf bound_ctrl:1
	v_fmac_f32_dpp v26, v34, v7 row_newbcast:10 row_mask:0xf bank_mask:0xf bound_ctrl:1
	v_fmac_f32_dpp v27, v34, v6 row_newbcast:11 row_mask:0xf bank_mask:0xf bound_ctrl:1
	v_fmac_f32_dpp v42, v34, v5 row_newbcast:12 row_mask:0xf bank_mask:0xf bound_ctrl:1
	v_readlane_b32 s97, v23, 0
	v_fmac_f32_dpp v25, v34, v4 row_newbcast:13 row_mask:0xf bank_mask:0xf bound_ctrl:1
	v_fmac_f32_dpp v26, v34, v3 row_newbcast:14 row_mask:0xf bank_mask:0xf bound_ctrl:1
	v_fmac_f32_dpp v27, v34, v2 row_newbcast:15 row_mask:0xf bank_mask:0xf bound_ctrl:1
	s_waitcnt lgkmcnt(2)
	v_fmac_f32_dpp v17, v36, v18 row_newbcast:0 row_mask:0xf bank_mask:0xf bound_ctrl:1
	v_fmac_f32_dpp v16, v36, v18 row_newbcast:1 row_mask:0xf bank_mask:0xf bound_ctrl:1
	v_fmac_f32_dpp v15, v36, v18 row_newbcast:2 row_mask:0xf bank_mask:0xf bound_ctrl:1
	v_fmac_f32_dpp v14, v36, v18 row_newbcast:3 row_mask:0xf bank_mask:0xf bound_ctrl:1
	v_fmac_f32_dpp v13, v36, v18 row_newbcast:4 row_mask:0xf bank_mask:0xf bound_ctrl:1
	v_fmac_f32_dpp v12, v36, v18 row_newbcast:5 row_mask:0xf bank_mask:0xf bound_ctrl:1
	v_fmac_f32_dpp v11, v36, v18 row_newbcast:6 row_mask:0xf bank_mask:0xf bound_ctrl:1
	v_fmac_f32_dpp v10, v36, v18 row_newbcast:7 row_mask:0xf bank_mask:0xf bound_ctrl:1
	v_fmac_f32_dpp v9, v36, v18 row_newbcast:8 row_mask:0xf bank_mask:0xf bound_ctrl:1
	v_fmac_f32_dpp v8, v36, v18 row_newbcast:9 row_mask:0xf bank_mask:0xf bound_ctrl:1
	v_fmac_f32_dpp v7, v36, v18 row_newbcast:10 row_mask:0xf bank_mask:0xf bound_ctrl:1
	v_fmac_f32_dpp v6, v36, v18 row_newbcast:11 row_mask:0xf bank_mask:0xf bound_ctrl:1
	v_fmac_f32_dpp v5, v36, v18 row_newbcast:12 row_mask:0xf bank_mask:0xf bound_ctrl:1
	v_fmac_f32_dpp v4, v36, v18 row_newbcast:13 row_mask:0xf bank_mask:0xf bound_ctrl:1
	v_fmac_f32_dpp v3, v36, v18 row_newbcast:14 row_mask:0xf bank_mask:0xf bound_ctrl:1
	v_fmac_f32_dpp v2, v36, v18 row_newbcast:15 row_mask:0xf bank_mask:0xf bound_ctrl:1
	v_add_f32 v42, v42, v25
	v_readlane_b32 vcc_hi, v23, 1
	v_readlane_b32 s96, v23, 2
	v_readlane_b32 s94, v23, 3
	v_readlane_b32 s92, v23, 4
	v_readlane_b32 s90, v23, 5
	v_readlane_b32 s88, v23, 6
	v_readlane_b32 s82, v23, 7
	v_readlane_b32 s80, v23, 8
	v_readlane_b32 s67, v23, 9
	v_readlane_b32 s65, v23, 10
	v_readlane_b32 s63, v23, 11
	v_readlane_b32 s59, v23, 12
	v_readlane_b32 s57, v23, 13
	v_readlane_b32 s53, v23, 14
	v_readlane_b32 s52, v23, 15
	v_add_f32 v26, v26, v27
	v_lshl_add_u32 v22, s48, 15, v134
	v_add_f32 v42, v42, v26
	s_nop 1
	v_mfma_f32_16x16x4_f32 v[224:227], v228, v42, 0
	v_readlane_b32 vcc_lo, v24, 0
	v_readlane_b32 s28, v24, 1
	v_readlane_b32 s95, v24, 2
	v_readlane_b32 s93, v24, 3
	v_readlane_b32 s91, v24, 4
	v_readlane_b32 s89, v24, 5
	v_readlane_b32 s83, v24, 6
	v_readlane_b32 s81, v24, 7
	v_readlane_b32 s79, v24, 8
	v_readlane_b32 s66, v24, 9
	v_readlane_b32 s64, v24, 10
	v_readlane_b32 s62, v24, 11
	v_readlane_b32 s58, v24, 12
	v_readlane_b32 s56, v24, 13
	v_readlane_b32 s48, v24, 14
	v_readlane_b32 s17, v24, 15
	s_waitcnt lgkmcnt(1)
	v_fmac_f32_dpp v17, v38, v32 row_newbcast:0 row_mask:0xf bank_mask:0xf bound_ctrl:1
	v_fmac_f32_dpp v16, v38, v32 row_newbcast:1 row_mask:0xf bank_mask:0xf bound_ctrl:1
	v_fmac_f32_dpp v15, v38, v32 row_newbcast:2 row_mask:0xf bank_mask:0xf bound_ctrl:1
	v_fmac_f32_dpp v14, v38, v32 row_newbcast:3 row_mask:0xf bank_mask:0xf bound_ctrl:1
	v_fmac_f32_dpp v13, v38, v32 row_newbcast:4 row_mask:0xf bank_mask:0xf bound_ctrl:1
	v_fmac_f32_dpp v12, v38, v32 row_newbcast:5 row_mask:0xf bank_mask:0xf bound_ctrl:1
	v_fmac_f32_dpp v11, v38, v32 row_newbcast:6 row_mask:0xf bank_mask:0xf bound_ctrl:1
	v_fmac_f32_dpp v10, v38, v32 row_newbcast:7 row_mask:0xf bank_mask:0xf bound_ctrl:1
	v_fmac_f32_dpp v9, v38, v32 row_newbcast:8 row_mask:0xf bank_mask:0xf bound_ctrl:1
	v_fmac_f32_dpp v8, v38, v32 row_newbcast:9 row_mask:0xf bank_mask:0xf bound_ctrl:1
	v_fmac_f32_dpp v7, v38, v32 row_newbcast:10 row_mask:0xf bank_mask:0xf bound_ctrl:1
	v_fmac_f32_dpp v6, v38, v32 row_newbcast:11 row_mask:0xf bank_mask:0xf bound_ctrl:1
	v_fmac_f32_dpp v5, v38, v32 row_newbcast:12 row_mask:0xf bank_mask:0xf bound_ctrl:1
	v_fmac_f32_dpp v4, v38, v32 row_newbcast:13 row_mask:0xf bank_mask:0xf bound_ctrl:1
	v_fmac_f32_dpp v3, v38, v32 row_newbcast:14 row_mask:0xf bank_mask:0xf bound_ctrl:1
	v_fmac_f32_dpp v2, v38, v32 row_newbcast:15 row_mask:0xf bank_mask:0xf bound_ctrl:1
	s_waitcnt lgkmcnt(0)
	v_mul_f32_dpp v24, v40, v17 row_newbcast:0 row_mask:0xf bank_mask:0xf bound_ctrl:1
	v_mul_f32_dpp v23, v40, v16 row_newbcast:1 row_mask:0xf bank_mask:0xf bound_ctrl:1
	v_mul_f32_dpp v25, v40, v15 row_newbcast:2 row_mask:0xf bank_mask:0xf bound_ctrl:1
	v_mul_f32_dpp v30, v40, v14 row_newbcast:3 row_mask:0xf bank_mask:0xf bound_ctrl:1
	v_fmac_f32_dpp v24, v40, v13 row_newbcast:4 row_mask:0xf bank_mask:0xf bound_ctrl:1
	v_fmac_f32_dpp v23, v40, v12 row_newbcast:5 row_mask:0xf bank_mask:0xf bound_ctrl:1
	v_fmac_f32_dpp v25, v40, v11 row_newbcast:6 row_mask:0xf bank_mask:0xf bound_ctrl:1
	v_fmac_f32_dpp v30, v40, v10 row_newbcast:7 row_mask:0xf bank_mask:0xf bound_ctrl:1
	v_add_u32_e32 v20, 0xc000, v22
	v_fmac_f32_dpp v24, v40, v9 row_newbcast:8 row_mask:0xf bank_mask:0xf bound_ctrl:1
	v_fmac_f32_dpp v23, v40, v8 row_newbcast:9 row_mask:0xf bank_mask:0xf bound_ctrl:1
	v_fmac_f32_dpp v25, v40, v7 row_newbcast:10 row_mask:0xf bank_mask:0xf bound_ctrl:1
	v_fmac_f32_dpp v30, v40, v6 row_newbcast:11 row_mask:0xf bank_mask:0xf bound_ctrl:1
	s_add_i32 s16, s16, 1
	v_fmac_f32_dpp v24, v40, v5 row_newbcast:12 row_mask:0xf bank_mask:0xf bound_ctrl:1
	v_fmac_f32_dpp v23, v40, v4 row_newbcast:13 row_mask:0xf bank_mask:0xf bound_ctrl:1
	v_fmac_f32_dpp v25, v40, v3 row_newbcast:14 row_mask:0xf bank_mask:0xf bound_ctrl:1
	v_fmac_f32_dpp v30, v40, v2 row_newbcast:15 row_mask:0xf bank_mask:0xf bound_ctrl:1
	v_mov_b32_e32 v42, v224
	ds_read_b32 v36, v19 offset:20992
	ds_read2st64_b32 v[26:27], v21 offset0:18 offset1:34
	ds_read2st64_b32 v[28:29], v21 offset0:50 offset1:66
	v_mul_f32_dpp v38, v35, v17 row_newbcast:0 row_mask:0xf bank_mask:0xf bound_ctrl:1
	v_mul_f32_dpp v31, v35, v16 row_newbcast:1 row_mask:0xf bank_mask:0xf bound_ctrl:1
	v_mul_f32_dpp v34, v35, v15 row_newbcast:2 row_mask:0xf bank_mask:0xf bound_ctrl:1
	v_mul_f32_dpp v40, v35, v14 row_newbcast:3 row_mask:0xf bank_mask:0xf bound_ctrl:1
	v_fmac_f32_e32 v42, s97, v18
	v_fmac_f32_dpp v38, v35, v13 row_newbcast:4 row_mask:0xf bank_mask:0xf bound_ctrl:1
	v_fmac_f32_dpp v31, v35, v12 row_newbcast:5 row_mask:0xf bank_mask:0xf bound_ctrl:1
	v_fmac_f32_dpp v34, v35, v11 row_newbcast:6 row_mask:0xf bank_mask:0xf bound_ctrl:1
	v_fmac_f32_dpp v40, v35, v10 row_newbcast:7 row_mask:0xf bank_mask:0xf bound_ctrl:1
	v_fmac_f32_e32 v42, vcc_lo, v32
	v_fmac_f32_dpp v38, v35, v9 row_newbcast:8 row_mask:0xf bank_mask:0xf bound_ctrl:1
	v_fmac_f32_dpp v31, v35, v8 row_newbcast:9 row_mask:0xf bank_mask:0xf bound_ctrl:1
	v_fmac_f32_dpp v34, v35, v7 row_newbcast:10 row_mask:0xf bank_mask:0xf bound_ctrl:1
	v_fmac_f32_dpp v40, v35, v6 row_newbcast:11 row_mask:0xf bank_mask:0xf bound_ctrl:1
	s_cmpk_lg_i32 s16, 0x210
	v_fmac_f32_dpp v38, v35, v5 row_newbcast:12 row_mask:0xf bank_mask:0xf bound_ctrl:1
	v_fmac_f32_dpp v31, v35, v4 row_newbcast:13 row_mask:0xf bank_mask:0xf bound_ctrl:1
	v_fmac_f32_dpp v34, v35, v3 row_newbcast:14 row_mask:0xf bank_mask:0xf bound_ctrl:1
	v_fmac_f32_dpp v40, v35, v2 row_newbcast:15 row_mask:0xf bank_mask:0xf bound_ctrl:1
	v_fmac_f32_dpp v17, v37, v42 row_newbcast:0 row_mask:0xf bank_mask:0xf bound_ctrl:1
	v_fmac_f32_dpp v16, v37, v42 row_newbcast:1 row_mask:0xf bank_mask:0xf bound_ctrl:1
	v_fmac_f32_dpp v15, v37, v42 row_newbcast:2 row_mask:0xf bank_mask:0xf bound_ctrl:1
	v_fmac_f32_dpp v14, v37, v42 row_newbcast:3 row_mask:0xf bank_mask:0xf bound_ctrl:1
	v_fmac_f32_dpp v13, v37, v42 row_newbcast:4 row_mask:0xf bank_mask:0xf bound_ctrl:1
	v_fmac_f32_dpp v12, v37, v42 row_newbcast:5 row_mask:0xf bank_mask:0xf bound_ctrl:1
	v_fmac_f32_dpp v11, v37, v42 row_newbcast:6 row_mask:0xf bank_mask:0xf bound_ctrl:1
	v_fmac_f32_dpp v10, v37, v42 row_newbcast:7 row_mask:0xf bank_mask:0xf bound_ctrl:1
	v_fmac_f32_dpp v9, v37, v42 row_newbcast:8 row_mask:0xf bank_mask:0xf bound_ctrl:1
	v_fmac_f32_dpp v8, v37, v42 row_newbcast:9 row_mask:0xf bank_mask:0xf bound_ctrl:1
	v_fmac_f32_dpp v7, v37, v42 row_newbcast:10 row_mask:0xf bank_mask:0xf bound_ctrl:1
	v_fmac_f32_dpp v6, v37, v42 row_newbcast:11 row_mask:0xf bank_mask:0xf bound_ctrl:1
	v_fmac_f32_dpp v5, v37, v42 row_newbcast:12 row_mask:0xf bank_mask:0xf bound_ctrl:1
	v_fmac_f32_dpp v4, v37, v42 row_newbcast:13 row_mask:0xf bank_mask:0xf bound_ctrl:1
	v_fmac_f32_dpp v3, v37, v42 row_newbcast:14 row_mask:0xf bank_mask:0xf bound_ctrl:1
	v_fmac_f32_dpp v2, v37, v42 row_newbcast:15 row_mask:0xf bank_mask:0xf bound_ctrl:1
	s_nop 0
	v_add_f32 v38, v38, v31
	v_add_f32 v34, v34, v40
	s_nop 0
	v_add_f32 v38, v38, v34
	v_add_f32 v24, v24, v23
	v_add_f32 v25, v25, v30
	v_mfma_f32_16x16x4_f32 v[224:227], v228, v38, 0
	ds_write_b64 v22, v[24:25] offset:49152
	v_fmac_f32_dpp v17, v39, v33 row_newbcast:0 row_mask:0xf bank_mask:0xf bound_ctrl:1
	v_fmac_f32_dpp v16, v39, v33 row_newbcast:1 row_mask:0xf bank_mask:0xf bound_ctrl:1
	v_fmac_f32_dpp v15, v39, v33 row_newbcast:2 row_mask:0xf bank_mask:0xf bound_ctrl:1
	v_fmac_f32_dpp v14, v39, v33 row_newbcast:3 row_mask:0xf bank_mask:0xf bound_ctrl:1
	v_fmac_f32_dpp v13, v39, v33 row_newbcast:4 row_mask:0xf bank_mask:0xf bound_ctrl:1
	v_fmac_f32_dpp v12, v39, v33 row_newbcast:5 row_mask:0xf bank_mask:0xf bound_ctrl:1
	v_fmac_f32_dpp v11, v39, v33 row_newbcast:6 row_mask:0xf bank_mask:0xf bound_ctrl:1
	v_fmac_f32_dpp v10, v39, v33 row_newbcast:7 row_mask:0xf bank_mask:0xf bound_ctrl:1
	v_fmac_f32_dpp v9, v39, v33 row_newbcast:8 row_mask:0xf bank_mask:0xf bound_ctrl:1
	v_fmac_f32_dpp v8, v39, v33 row_newbcast:9 row_mask:0xf bank_mask:0xf bound_ctrl:1
	v_fmac_f32_dpp v7, v39, v33 row_newbcast:10 row_mask:0xf bank_mask:0xf bound_ctrl:1
	v_fmac_f32_dpp v6, v39, v33 row_newbcast:11 row_mask:0xf bank_mask:0xf bound_ctrl:1
	v_fmac_f32_dpp v5, v39, v33 row_newbcast:12 row_mask:0xf bank_mask:0xf bound_ctrl:1
	v_fmac_f32_dpp v4, v39, v33 row_newbcast:13 row_mask:0xf bank_mask:0xf bound_ctrl:1
	v_fmac_f32_dpp v3, v39, v33 row_newbcast:14 row_mask:0xf bank_mask:0xf bound_ctrl:1
	v_fmac_f32_dpp v2, v39, v33 row_newbcast:15 row_mask:0xf bank_mask:0xf bound_ctrl:1
	v_mul_f32_dpp v24, v41, v17 row_newbcast:0 row_mask:0xf bank_mask:0xf bound_ctrl:1
	v_mul_f32_dpp v18, v41, v16 row_newbcast:1 row_mask:0xf bank_mask:0xf bound_ctrl:1
	v_mul_f32_dpp v25, v41, v15 row_newbcast:2 row_mask:0xf bank_mask:0xf bound_ctrl:1
	v_mul_f32_dpp v23, v41, v14 row_newbcast:3 row_mask:0xf bank_mask:0xf bound_ctrl:1
	v_fmac_f32_dpp v24, v41, v13 row_newbcast:4 row_mask:0xf bank_mask:0xf bound_ctrl:1
	v_fmac_f32_dpp v18, v41, v12 row_newbcast:5 row_mask:0xf bank_mask:0xf bound_ctrl:1
	v_fmac_f32_dpp v25, v41, v11 row_newbcast:6 row_mask:0xf bank_mask:0xf bound_ctrl:1
	v_fmac_f32_dpp v23, v41, v10 row_newbcast:7 row_mask:0xf bank_mask:0xf bound_ctrl:1
	s_nop 0
	v_fmac_f32_dpp v24, v41, v9 row_newbcast:8 row_mask:0xf bank_mask:0xf bound_ctrl:1
	v_fmac_f32_dpp v18, v41, v8 row_newbcast:9 row_mask:0xf bank_mask:0xf bound_ctrl:1
	v_fmac_f32_dpp v25, v41, v7 row_newbcast:10 row_mask:0xf bank_mask:0xf bound_ctrl:1
	v_fmac_f32_dpp v23, v41, v6 row_newbcast:11 row_mask:0xf bank_mask:0xf bound_ctrl:1
	s_nop 0
	v_fmac_f32_dpp v24, v41, v5 row_newbcast:12 row_mask:0xf bank_mask:0xf bound_ctrl:1
	v_fmac_f32_dpp v18, v41, v4 row_newbcast:13 row_mask:0xf bank_mask:0xf bound_ctrl:1
	v_fmac_f32_dpp v25, v41, v3 row_newbcast:14 row_mask:0xf bank_mask:0xf bound_ctrl:1
	v_fmac_f32_dpp v23, v41, v2 row_newbcast:15 row_mask:0xf bank_mask:0xf bound_ctrl:1
	s_waitcnt lgkmcnt(0)
	v_mov_b32_e32 v38, v224
	ds_read_b32 v37, v19 offset:21248
	ds_read2st64_b32 v[30:31], v21 offset0:19 offset1:35
	ds_read2st64_b32 v[34:35], v21 offset0:51 offset1:67
	v_mul_f32_dpp v39, v26, v17 row_newbcast:0 row_mask:0xf bank_mask:0xf bound_ctrl:1
	v_mul_f32_dpp v32, v26, v16 row_newbcast:1 row_mask:0xf bank_mask:0xf bound_ctrl:1
	v_mul_f32_dpp v40, v26, v15 row_newbcast:2 row_mask:0xf bank_mask:0xf bound_ctrl:1
	v_mul_f32_dpp v41, v26, v14 row_newbcast:3 row_mask:0xf bank_mask:0xf bound_ctrl:1
	v_fmac_f32_e32 v38, vcc_hi, v42
	v_fmac_f32_dpp v39, v26, v13 row_newbcast:4 row_mask:0xf bank_mask:0xf bound_ctrl:1
	v_fmac_f32_dpp v32, v26, v12 row_newbcast:5 row_mask:0xf bank_mask:0xf bound_ctrl:1
	v_fmac_f32_dpp v40, v26, v11 row_newbcast:6 row_mask:0xf bank_mask:0xf bound_ctrl:1
	v_fmac_f32_dpp v41, v26, v10 row_newbcast:7 row_mask:0xf bank_mask:0xf bound_ctrl:1
	v_fmac_f32_e32 v38, s28, v33
	v_fmac_f32_dpp v39, v26, v9 row_newbcast:8 row_mask:0xf bank_mask:0xf bound_ctrl:1
	v_fmac_f32_dpp v32, v26, v8 row_newbcast:9 row_mask:0xf bank_mask:0xf bound_ctrl:1
	v_fmac_f32_dpp v40, v26, v7 row_newbcast:10 row_mask:0xf bank_mask:0xf bound_ctrl:1
	v_fmac_f32_dpp v41, v26, v6 row_newbcast:11 row_mask:0xf bank_mask:0xf bound_ctrl:1
	s_nop 0
	v_fmac_f32_dpp v39, v26, v5 row_newbcast:12 row_mask:0xf bank_mask:0xf bound_ctrl:1
	v_fmac_f32_dpp v32, v26, v4 row_newbcast:13 row_mask:0xf bank_mask:0xf bound_ctrl:1
	v_fmac_f32_dpp v40, v26, v3 row_newbcast:14 row_mask:0xf bank_mask:0xf bound_ctrl:1
	v_fmac_f32_dpp v41, v26, v2 row_newbcast:15 row_mask:0xf bank_mask:0xf bound_ctrl:1
	v_fmac_f32_dpp v17, v27, v38 row_newbcast:0 row_mask:0xf bank_mask:0xf bound_ctrl:1
	v_fmac_f32_dpp v16, v27, v38 row_newbcast:1 row_mask:0xf bank_mask:0xf bound_ctrl:1
	v_fmac_f32_dpp v15, v27, v38 row_newbcast:2 row_mask:0xf bank_mask:0xf bound_ctrl:1
	v_fmac_f32_dpp v14, v27, v38 row_newbcast:3 row_mask:0xf bank_mask:0xf bound_ctrl:1
	v_fmac_f32_dpp v13, v27, v38 row_newbcast:4 row_mask:0xf bank_mask:0xf bound_ctrl:1
	v_fmac_f32_dpp v12, v27, v38 row_newbcast:5 row_mask:0xf bank_mask:0xf bound_ctrl:1
	v_fmac_f32_dpp v11, v27, v38 row_newbcast:6 row_mask:0xf bank_mask:0xf bound_ctrl:1
	v_fmac_f32_dpp v10, v27, v38 row_newbcast:7 row_mask:0xf bank_mask:0xf bound_ctrl:1
	v_fmac_f32_dpp v9, v27, v38 row_newbcast:8 row_mask:0xf bank_mask:0xf bound_ctrl:1
	v_fmac_f32_dpp v8, v27, v38 row_newbcast:9 row_mask:0xf bank_mask:0xf bound_ctrl:1
	v_fmac_f32_dpp v7, v27, v38 row_newbcast:10 row_mask:0xf bank_mask:0xf bound_ctrl:1
	v_fmac_f32_dpp v6, v27, v38 row_newbcast:11 row_mask:0xf bank_mask:0xf bound_ctrl:1
	v_fmac_f32_dpp v5, v27, v38 row_newbcast:12 row_mask:0xf bank_mask:0xf bound_ctrl:1
	v_fmac_f32_dpp v4, v27, v38 row_newbcast:13 row_mask:0xf bank_mask:0xf bound_ctrl:1
	v_fmac_f32_dpp v3, v27, v38 row_newbcast:14 row_mask:0xf bank_mask:0xf bound_ctrl:1
	v_fmac_f32_dpp v2, v27, v38 row_newbcast:15 row_mask:0xf bank_mask:0xf bound_ctrl:1
	s_nop 0
	v_add_f32 v39, v39, v32
	v_add_f32 v40, v40, v41
	s_nop 0
	v_add_f32 v39, v39, v40
	v_add_f32 v24, v24, v18
	v_add_f32 v25, v25, v23
	v_mfma_f32_16x16x4_f32 v[224:227], v228, v39, 0
	ds_write_b64 v22, v[24:25] offset:51200
	v_fmac_f32_dpp v17, v28, v36 row_newbcast:0 row_mask:0xf bank_mask:0xf bound_ctrl:1
	v_fmac_f32_dpp v16, v28, v36 row_newbcast:1 row_mask:0xf bank_mask:0xf bound_ctrl:1
	v_fmac_f32_dpp v15, v28, v36 row_newbcast:2 row_mask:0xf bank_mask:0xf bound_ctrl:1
	v_fmac_f32_dpp v14, v28, v36 row_newbcast:3 row_mask:0xf bank_mask:0xf bound_ctrl:1
	v_fmac_f32_dpp v13, v28, v36 row_newbcast:4 row_mask:0xf bank_mask:0xf bound_ctrl:1
	v_fmac_f32_dpp v12, v28, v36 row_newbcast:5 row_mask:0xf bank_mask:0xf bound_ctrl:1
	v_fmac_f32_dpp v11, v28, v36 row_newbcast:6 row_mask:0xf bank_mask:0xf bound_ctrl:1
	v_fmac_f32_dpp v10, v28, v36 row_newbcast:7 row_mask:0xf bank_mask:0xf bound_ctrl:1
	v_fmac_f32_dpp v9, v28, v36 row_newbcast:8 row_mask:0xf bank_mask:0xf bound_ctrl:1
	v_fmac_f32_dpp v8, v28, v36 row_newbcast:9 row_mask:0xf bank_mask:0xf bound_ctrl:1
	v_fmac_f32_dpp v7, v28, v36 row_newbcast:10 row_mask:0xf bank_mask:0xf bound_ctrl:1
	v_fmac_f32_dpp v6, v28, v36 row_newbcast:11 row_mask:0xf bank_mask:0xf bound_ctrl:1
	v_fmac_f32_dpp v5, v28, v36 row_newbcast:12 row_mask:0xf bank_mask:0xf bound_ctrl:1
	v_fmac_f32_dpp v4, v28, v36 row_newbcast:13 row_mask:0xf bank_mask:0xf bound_ctrl:1
	v_fmac_f32_dpp v3, v28, v36 row_newbcast:14 row_mask:0xf bank_mask:0xf bound_ctrl:1
	v_fmac_f32_dpp v2, v28, v36 row_newbcast:15 row_mask:0xf bank_mask:0xf bound_ctrl:1
	v_mul_f32_dpp v24, v29, v17 row_newbcast:0 row_mask:0xf bank_mask:0xf bound_ctrl:1
	v_mul_f32_dpp v18, v29, v16 row_newbcast:1 row_mask:0xf bank_mask:0xf bound_ctrl:1
	v_mul_f32_dpp v25, v29, v15 row_newbcast:2 row_mask:0xf bank_mask:0xf bound_ctrl:1
	v_mul_f32_dpp v23, v29, v14 row_newbcast:3 row_mask:0xf bank_mask:0xf bound_ctrl:1
	v_fmac_f32_dpp v24, v29, v13 row_newbcast:4 row_mask:0xf bank_mask:0xf bound_ctrl:1
	v_fmac_f32_dpp v18, v29, v12 row_newbcast:5 row_mask:0xf bank_mask:0xf bound_ctrl:1
	v_fmac_f32_dpp v25, v29, v11 row_newbcast:6 row_mask:0xf bank_mask:0xf bound_ctrl:1
	v_fmac_f32_dpp v23, v29, v10 row_newbcast:7 row_mask:0xf bank_mask:0xf bound_ctrl:1
	s_nop 0
	v_fmac_f32_dpp v24, v29, v9 row_newbcast:8 row_mask:0xf bank_mask:0xf bound_ctrl:1
	v_fmac_f32_dpp v18, v29, v8 row_newbcast:9 row_mask:0xf bank_mask:0xf bound_ctrl:1
	v_fmac_f32_dpp v25, v29, v7 row_newbcast:10 row_mask:0xf bank_mask:0xf bound_ctrl:1
	v_fmac_f32_dpp v23, v29, v6 row_newbcast:11 row_mask:0xf bank_mask:0xf bound_ctrl:1
	s_nop 0
	v_fmac_f32_dpp v24, v29, v5 row_newbcast:12 row_mask:0xf bank_mask:0xf bound_ctrl:1
	v_fmac_f32_dpp v18, v29, v4 row_newbcast:13 row_mask:0xf bank_mask:0xf bound_ctrl:1
	v_fmac_f32_dpp v25, v29, v3 row_newbcast:14 row_mask:0xf bank_mask:0xf bound_ctrl:1
	v_fmac_f32_dpp v23, v29, v2 row_newbcast:15 row_mask:0xf bank_mask:0xf bound_ctrl:1
	s_waitcnt lgkmcnt(0)
	v_mov_b32_e32 v39, v224
	ds_read_b32 v40, v19 offset:21504
	ds_read2st64_b32 v[26:27], v21 offset0:20 offset1:36
	ds_read2st64_b32 v[28:29], v21 offset0:52 offset1:68
	v_mul_f32_dpp v41, v30, v17 row_newbcast:0 row_mask:0xf bank_mask:0xf bound_ctrl:1
	v_mul_f32_dpp v32, v30, v16 row_newbcast:1 row_mask:0xf bank_mask:0xf bound_ctrl:1
	v_mul_f32_dpp v33, v30, v15 row_newbcast:2 row_mask:0xf bank_mask:0xf bound_ctrl:1
	v_mul_f32_dpp v42, v30, v14 row_newbcast:3 row_mask:0xf bank_mask:0xf bound_ctrl:1
	v_fmac_f32_e32 v39, s96, v38
	v_fmac_f32_dpp v41, v30, v13 row_newbcast:4 row_mask:0xf bank_mask:0xf bound_ctrl:1
	v_fmac_f32_dpp v32, v30, v12 row_newbcast:5 row_mask:0xf bank_mask:0xf bound_ctrl:1
	v_fmac_f32_dpp v33, v30, v11 row_newbcast:6 row_mask:0xf bank_mask:0xf bound_ctrl:1
	v_fmac_f32_dpp v42, v30, v10 row_newbcast:7 row_mask:0xf bank_mask:0xf bound_ctrl:1
	v_fmac_f32_e32 v39, s95, v36
	v_fmac_f32_dpp v41, v30, v9 row_newbcast:8 row_mask:0xf bank_mask:0xf bound_ctrl:1
	v_fmac_f32_dpp v32, v30, v8 row_newbcast:9 row_mask:0xf bank_mask:0xf bound_ctrl:1
	v_fmac_f32_dpp v33, v30, v7 row_newbcast:10 row_mask:0xf bank_mask:0xf bound_ctrl:1
	v_fmac_f32_dpp v42, v30, v6 row_newbcast:11 row_mask:0xf bank_mask:0xf bound_ctrl:1
	s_nop 0
	v_fmac_f32_dpp v41, v30, v5 row_newbcast:12 row_mask:0xf bank_mask:0xf bound_ctrl:1
	v_fmac_f32_dpp v32, v30, v4 row_newbcast:13 row_mask:0xf bank_mask:0xf bound_ctrl:1
	v_fmac_f32_dpp v33, v30, v3 row_newbcast:14 row_mask:0xf bank_mask:0xf bound_ctrl:1
	v_fmac_f32_dpp v42, v30, v2 row_newbcast:15 row_mask:0xf bank_mask:0xf bound_ctrl:1
	v_fmac_f32_dpp v17, v31, v39 row_newbcast:0 row_mask:0xf bank_mask:0xf bound_ctrl:1
	v_fmac_f32_dpp v16, v31, v39 row_newbcast:1 row_mask:0xf bank_mask:0xf bound_ctrl:1
	v_fmac_f32_dpp v15, v31, v39 row_newbcast:2 row_mask:0xf bank_mask:0xf bound_ctrl:1
	v_fmac_f32_dpp v14, v31, v39 row_newbcast:3 row_mask:0xf bank_mask:0xf bound_ctrl:1
	v_fmac_f32_dpp v13, v31, v39 row_newbcast:4 row_mask:0xf bank_mask:0xf bound_ctrl:1
	v_fmac_f32_dpp v12, v31, v39 row_newbcast:5 row_mask:0xf bank_mask:0xf bound_ctrl:1
	v_fmac_f32_dpp v11, v31, v39 row_newbcast:6 row_mask:0xf bank_mask:0xf bound_ctrl:1
	v_fmac_f32_dpp v10, v31, v39 row_newbcast:7 row_mask:0xf bank_mask:0xf bound_ctrl:1
	v_fmac_f32_dpp v9, v31, v39 row_newbcast:8 row_mask:0xf bank_mask:0xf bound_ctrl:1
	v_fmac_f32_dpp v8, v31, v39 row_newbcast:9 row_mask:0xf bank_mask:0xf bound_ctrl:1
	v_fmac_f32_dpp v7, v31, v39 row_newbcast:10 row_mask:0xf bank_mask:0xf bound_ctrl:1
	v_fmac_f32_dpp v6, v31, v39 row_newbcast:11 row_mask:0xf bank_mask:0xf bound_ctrl:1
	v_fmac_f32_dpp v5, v31, v39 row_newbcast:12 row_mask:0xf bank_mask:0xf bound_ctrl:1
	v_fmac_f32_dpp v4, v31, v39 row_newbcast:13 row_mask:0xf bank_mask:0xf bound_ctrl:1
	v_fmac_f32_dpp v3, v31, v39 row_newbcast:14 row_mask:0xf bank_mask:0xf bound_ctrl:1
	v_fmac_f32_dpp v2, v31, v39 row_newbcast:15 row_mask:0xf bank_mask:0xf bound_ctrl:1
	s_nop 0
	v_add_f32 v41, v41, v32
	v_add_f32 v33, v33, v42
	s_nop 0
	v_add_f32 v41, v41, v33
	v_add_f32 v24, v24, v18
	v_add_f32 v25, v25, v23
	v_mfma_f32_16x16x4_f32 v[224:227], v228, v41, 0
	ds_write_b64 v22, v[24:25] offset:53248
	v_fmac_f32_dpp v17, v34, v37 row_newbcast:0 row_mask:0xf bank_mask:0xf bound_ctrl:1
	v_fmac_f32_dpp v16, v34, v37 row_newbcast:1 row_mask:0xf bank_mask:0xf bound_ctrl:1
	v_fmac_f32_dpp v15, v34, v37 row_newbcast:2 row_mask:0xf bank_mask:0xf bound_ctrl:1
	v_fmac_f32_dpp v14, v34, v37 row_newbcast:3 row_mask:0xf bank_mask:0xf bound_ctrl:1
	v_fmac_f32_dpp v13, v34, v37 row_newbcast:4 row_mask:0xf bank_mask:0xf bound_ctrl:1
	v_fmac_f32_dpp v12, v34, v37 row_newbcast:5 row_mask:0xf bank_mask:0xf bound_ctrl:1
	v_fmac_f32_dpp v11, v34, v37 row_newbcast:6 row_mask:0xf bank_mask:0xf bound_ctrl:1
	v_fmac_f32_dpp v10, v34, v37 row_newbcast:7 row_mask:0xf bank_mask:0xf bound_ctrl:1
	v_fmac_f32_dpp v9, v34, v37 row_newbcast:8 row_mask:0xf bank_mask:0xf bound_ctrl:1
	v_fmac_f32_dpp v8, v34, v37 row_newbcast:9 row_mask:0xf bank_mask:0xf bound_ctrl:1
	v_fmac_f32_dpp v7, v34, v37 row_newbcast:10 row_mask:0xf bank_mask:0xf bound_ctrl:1
	v_fmac_f32_dpp v6, v34, v37 row_newbcast:11 row_mask:0xf bank_mask:0xf bound_ctrl:1
	v_fmac_f32_dpp v5, v34, v37 row_newbcast:12 row_mask:0xf bank_mask:0xf bound_ctrl:1
	v_fmac_f32_dpp v4, v34, v37 row_newbcast:13 row_mask:0xf bank_mask:0xf bound_ctrl:1
	v_fmac_f32_dpp v3, v34, v37 row_newbcast:14 row_mask:0xf bank_mask:0xf bound_ctrl:1
	v_fmac_f32_dpp v2, v34, v37 row_newbcast:15 row_mask:0xf bank_mask:0xf bound_ctrl:1
	v_mul_f32_dpp v24, v35, v17 row_newbcast:0 row_mask:0xf bank_mask:0xf bound_ctrl:1
	v_mul_f32_dpp v18, v35, v16 row_newbcast:1 row_mask:0xf bank_mask:0xf bound_ctrl:1
	v_mul_f32_dpp v25, v35, v15 row_newbcast:2 row_mask:0xf bank_mask:0xf bound_ctrl:1
	v_mul_f32_dpp v23, v35, v14 row_newbcast:3 row_mask:0xf bank_mask:0xf bound_ctrl:1
	v_fmac_f32_dpp v24, v35, v13 row_newbcast:4 row_mask:0xf bank_mask:0xf bound_ctrl:1
	v_fmac_f32_dpp v18, v35, v12 row_newbcast:5 row_mask:0xf bank_mask:0xf bound_ctrl:1
	v_fmac_f32_dpp v25, v35, v11 row_newbcast:6 row_mask:0xf bank_mask:0xf bound_ctrl:1
	v_fmac_f32_dpp v23, v35, v10 row_newbcast:7 row_mask:0xf bank_mask:0xf bound_ctrl:1
	s_nop 0
	v_fmac_f32_dpp v24, v35, v9 row_newbcast:8 row_mask:0xf bank_mask:0xf bound_ctrl:1
	v_fmac_f32_dpp v18, v35, v8 row_newbcast:9 row_mask:0xf bank_mask:0xf bound_ctrl:1
	v_fmac_f32_dpp v25, v35, v7 row_newbcast:10 row_mask:0xf bank_mask:0xf bound_ctrl:1
	v_fmac_f32_dpp v23, v35, v6 row_newbcast:11 row_mask:0xf bank_mask:0xf bound_ctrl:1
	s_nop 0
	v_fmac_f32_dpp v24, v35, v5 row_newbcast:12 row_mask:0xf bank_mask:0xf bound_ctrl:1
	v_fmac_f32_dpp v18, v35, v4 row_newbcast:13 row_mask:0xf bank_mask:0xf bound_ctrl:1
	v_fmac_f32_dpp v25, v35, v3 row_newbcast:14 row_mask:0xf bank_mask:0xf bound_ctrl:1
	v_fmac_f32_dpp v23, v35, v2 row_newbcast:15 row_mask:0xf bank_mask:0xf bound_ctrl:1
	s_waitcnt lgkmcnt(0)
	v_mov_b32_e32 v41, v224
	ds_read_b32 v34, v19 offset:21760
	ds_read2st64_b32 v[30:31], v21 offset0:21 offset1:37
	ds_read2st64_b32 v[32:33], v21 offset0:53 offset1:69
	v_mul_f32_dpp v35, v26, v17 row_newbcast:0 row_mask:0xf bank_mask:0xf bound_ctrl:1
	v_mul_f32_dpp v36, v26, v16 row_newbcast:1 row_mask:0xf bank_mask:0xf bound_ctrl:1
	v_mul_f32_dpp v38, v26, v15 row_newbcast:2 row_mask:0xf bank_mask:0xf bound_ctrl:1
	v_mul_f32_dpp v42, v26, v14 row_newbcast:3 row_mask:0xf bank_mask:0xf bound_ctrl:1
	v_fmac_f32_e32 v41, s94, v39
	v_fmac_f32_dpp v35, v26, v13 row_newbcast:4 row_mask:0xf bank_mask:0xf bound_ctrl:1
	v_fmac_f32_dpp v36, v26, v12 row_newbcast:5 row_mask:0xf bank_mask:0xf bound_ctrl:1
	v_fmac_f32_dpp v38, v26, v11 row_newbcast:6 row_mask:0xf bank_mask:0xf bound_ctrl:1
	v_fmac_f32_dpp v42, v26, v10 row_newbcast:7 row_mask:0xf bank_mask:0xf bound_ctrl:1
	v_fmac_f32_e32 v41, s93, v37
	v_fmac_f32_dpp v35, v26, v9 row_newbcast:8 row_mask:0xf bank_mask:0xf bound_ctrl:1
	v_fmac_f32_dpp v36, v26, v8 row_newbcast:9 row_mask:0xf bank_mask:0xf bound_ctrl:1
	v_fmac_f32_dpp v38, v26, v7 row_newbcast:10 row_mask:0xf bank_mask:0xf bound_ctrl:1
	v_fmac_f32_dpp v42, v26, v6 row_newbcast:11 row_mask:0xf bank_mask:0xf bound_ctrl:1
	s_nop 0
	v_fmac_f32_dpp v35, v26, v5 row_newbcast:12 row_mask:0xf bank_mask:0xf bound_ctrl:1
	v_fmac_f32_dpp v36, v26, v4 row_newbcast:13 row_mask:0xf bank_mask:0xf bound_ctrl:1
	v_fmac_f32_dpp v38, v26, v3 row_newbcast:14 row_mask:0xf bank_mask:0xf bound_ctrl:1
	v_fmac_f32_dpp v42, v26, v2 row_newbcast:15 row_mask:0xf bank_mask:0xf bound_ctrl:1
	v_fmac_f32_dpp v17, v27, v41 row_newbcast:0 row_mask:0xf bank_mask:0xf bound_ctrl:1
	v_fmac_f32_dpp v16, v27, v41 row_newbcast:1 row_mask:0xf bank_mask:0xf bound_ctrl:1
	v_fmac_f32_dpp v15, v27, v41 row_newbcast:2 row_mask:0xf bank_mask:0xf bound_ctrl:1
	v_fmac_f32_dpp v14, v27, v41 row_newbcast:3 row_mask:0xf bank_mask:0xf bound_ctrl:1
	v_fmac_f32_dpp v13, v27, v41 row_newbcast:4 row_mask:0xf bank_mask:0xf bound_ctrl:1
	v_fmac_f32_dpp v12, v27, v41 row_newbcast:5 row_mask:0xf bank_mask:0xf bound_ctrl:1
	v_fmac_f32_dpp v11, v27, v41 row_newbcast:6 row_mask:0xf bank_mask:0xf bound_ctrl:1
	v_fmac_f32_dpp v10, v27, v41 row_newbcast:7 row_mask:0xf bank_mask:0xf bound_ctrl:1
	v_fmac_f32_dpp v9, v27, v41 row_newbcast:8 row_mask:0xf bank_mask:0xf bound_ctrl:1
	v_fmac_f32_dpp v8, v27, v41 row_newbcast:9 row_mask:0xf bank_mask:0xf bound_ctrl:1
	v_fmac_f32_dpp v7, v27, v41 row_newbcast:10 row_mask:0xf bank_mask:0xf bound_ctrl:1
	v_fmac_f32_dpp v6, v27, v41 row_newbcast:11 row_mask:0xf bank_mask:0xf bound_ctrl:1
	v_fmac_f32_dpp v5, v27, v41 row_newbcast:12 row_mask:0xf bank_mask:0xf bound_ctrl:1
	v_fmac_f32_dpp v4, v27, v41 row_newbcast:13 row_mask:0xf bank_mask:0xf bound_ctrl:1
	v_fmac_f32_dpp v3, v27, v41 row_newbcast:14 row_mask:0xf bank_mask:0xf bound_ctrl:1
	v_fmac_f32_dpp v2, v27, v41 row_newbcast:15 row_mask:0xf bank_mask:0xf bound_ctrl:1
	s_nop 0
	v_add_f32 v35, v35, v36
	v_add_f32 v38, v38, v42
	s_nop 0
	v_add_f32 v35, v35, v38
	v_add_f32 v24, v24, v18
	v_add_f32 v25, v25, v23
	v_mfma_f32_16x16x4_f32 v[224:227], v228, v35, 0
	ds_write_b64 v22, v[24:25] offset:55296
	v_fmac_f32_dpp v17, v28, v40 row_newbcast:0 row_mask:0xf bank_mask:0xf bound_ctrl:1
	v_fmac_f32_dpp v16, v28, v40 row_newbcast:1 row_mask:0xf bank_mask:0xf bound_ctrl:1
	v_fmac_f32_dpp v15, v28, v40 row_newbcast:2 row_mask:0xf bank_mask:0xf bound_ctrl:1
	v_fmac_f32_dpp v14, v28, v40 row_newbcast:3 row_mask:0xf bank_mask:0xf bound_ctrl:1
	v_fmac_f32_dpp v13, v28, v40 row_newbcast:4 row_mask:0xf bank_mask:0xf bound_ctrl:1
	v_fmac_f32_dpp v12, v28, v40 row_newbcast:5 row_mask:0xf bank_mask:0xf bound_ctrl:1
	v_fmac_f32_dpp v11, v28, v40 row_newbcast:6 row_mask:0xf bank_mask:0xf bound_ctrl:1
	v_fmac_f32_dpp v10, v28, v40 row_newbcast:7 row_mask:0xf bank_mask:0xf bound_ctrl:1
	v_fmac_f32_dpp v9, v28, v40 row_newbcast:8 row_mask:0xf bank_mask:0xf bound_ctrl:1
	v_fmac_f32_dpp v8, v28, v40 row_newbcast:9 row_mask:0xf bank_mask:0xf bound_ctrl:1
	v_fmac_f32_dpp v7, v28, v40 row_newbcast:10 row_mask:0xf bank_mask:0xf bound_ctrl:1
	v_fmac_f32_dpp v6, v28, v40 row_newbcast:11 row_mask:0xf bank_mask:0xf bound_ctrl:1
	v_fmac_f32_dpp v5, v28, v40 row_newbcast:12 row_mask:0xf bank_mask:0xf bound_ctrl:1
	v_fmac_f32_dpp v4, v28, v40 row_newbcast:13 row_mask:0xf bank_mask:0xf bound_ctrl:1
	v_fmac_f32_dpp v3, v28, v40 row_newbcast:14 row_mask:0xf bank_mask:0xf bound_ctrl:1
	v_fmac_f32_dpp v2, v28, v40 row_newbcast:15 row_mask:0xf bank_mask:0xf bound_ctrl:1
	v_mul_f32_dpp v24, v29, v17 row_newbcast:0 row_mask:0xf bank_mask:0xf bound_ctrl:1
	v_mul_f32_dpp v18, v29, v16 row_newbcast:1 row_mask:0xf bank_mask:0xf bound_ctrl:1
	v_mul_f32_dpp v25, v29, v15 row_newbcast:2 row_mask:0xf bank_mask:0xf bound_ctrl:1
	v_mul_f32_dpp v23, v29, v14 row_newbcast:3 row_mask:0xf bank_mask:0xf bound_ctrl:1
	v_fmac_f32_dpp v24, v29, v13 row_newbcast:4 row_mask:0xf bank_mask:0xf bound_ctrl:1
	v_fmac_f32_dpp v18, v29, v12 row_newbcast:5 row_mask:0xf bank_mask:0xf bound_ctrl:1
	v_fmac_f32_dpp v25, v29, v11 row_newbcast:6 row_mask:0xf bank_mask:0xf bound_ctrl:1
	v_fmac_f32_dpp v23, v29, v10 row_newbcast:7 row_mask:0xf bank_mask:0xf bound_ctrl:1
	s_nop 0
	v_fmac_f32_dpp v24, v29, v9 row_newbcast:8 row_mask:0xf bank_mask:0xf bound_ctrl:1
	v_fmac_f32_dpp v18, v29, v8 row_newbcast:9 row_mask:0xf bank_mask:0xf bound_ctrl:1
	v_fmac_f32_dpp v25, v29, v7 row_newbcast:10 row_mask:0xf bank_mask:0xf bound_ctrl:1
	v_fmac_f32_dpp v23, v29, v6 row_newbcast:11 row_mask:0xf bank_mask:0xf bound_ctrl:1
	s_nop 0
	v_fmac_f32_dpp v24, v29, v5 row_newbcast:12 row_mask:0xf bank_mask:0xf bound_ctrl:1
	v_fmac_f32_dpp v18, v29, v4 row_newbcast:13 row_mask:0xf bank_mask:0xf bound_ctrl:1
	v_fmac_f32_dpp v25, v29, v3 row_newbcast:14 row_mask:0xf bank_mask:0xf bound_ctrl:1
	v_fmac_f32_dpp v23, v29, v2 row_newbcast:15 row_mask:0xf bank_mask:0xf bound_ctrl:1
	s_waitcnt lgkmcnt(0)
	v_mov_b32_e32 v35, v224
	ds_read_b32 v36, v19 offset:22016
	ds_read2st64_b32 v[26:27], v21 offset0:22 offset1:38
	ds_read2st64_b32 v[28:29], v21 offset0:54 offset1:70
	v_mul_f32_dpp v37, v30, v17 row_newbcast:0 row_mask:0xf bank_mask:0xf bound_ctrl:1
	v_mul_f32_dpp v38, v30, v16 row_newbcast:1 row_mask:0xf bank_mask:0xf bound_ctrl:1
	v_mul_f32_dpp v39, v30, v15 row_newbcast:2 row_mask:0xf bank_mask:0xf bound_ctrl:1
	v_mul_f32_dpp v42, v30, v14 row_newbcast:3 row_mask:0xf bank_mask:0xf bound_ctrl:1
	v_fmac_f32_e32 v35, s92, v41
	v_fmac_f32_dpp v37, v30, v13 row_newbcast:4 row_mask:0xf bank_mask:0xf bound_ctrl:1
	v_fmac_f32_dpp v38, v30, v12 row_newbcast:5 row_mask:0xf bank_mask:0xf bound_ctrl:1
	v_fmac_f32_dpp v39, v30, v11 row_newbcast:6 row_mask:0xf bank_mask:0xf bound_ctrl:1
	v_fmac_f32_dpp v42, v30, v10 row_newbcast:7 row_mask:0xf bank_mask:0xf bound_ctrl:1
	v_fmac_f32_e32 v35, s91, v40
	v_fmac_f32_dpp v37, v30, v9 row_newbcast:8 row_mask:0xf bank_mask:0xf bound_ctrl:1
	v_fmac_f32_dpp v38, v30, v8 row_newbcast:9 row_mask:0xf bank_mask:0xf bound_ctrl:1
	v_fmac_f32_dpp v39, v30, v7 row_newbcast:10 row_mask:0xf bank_mask:0xf bound_ctrl:1
	v_fmac_f32_dpp v42, v30, v6 row_newbcast:11 row_mask:0xf bank_mask:0xf bound_ctrl:1
	s_nop 0
	v_fmac_f32_dpp v37, v30, v5 row_newbcast:12 row_mask:0xf bank_mask:0xf bound_ctrl:1
	v_fmac_f32_dpp v38, v30, v4 row_newbcast:13 row_mask:0xf bank_mask:0xf bound_ctrl:1
	v_fmac_f32_dpp v39, v30, v3 row_newbcast:14 row_mask:0xf bank_mask:0xf bound_ctrl:1
	v_fmac_f32_dpp v42, v30, v2 row_newbcast:15 row_mask:0xf bank_mask:0xf bound_ctrl:1
	v_fmac_f32_dpp v17, v31, v35 row_newbcast:0 row_mask:0xf bank_mask:0xf bound_ctrl:1
	v_fmac_f32_dpp v16, v31, v35 row_newbcast:1 row_mask:0xf bank_mask:0xf bound_ctrl:1
	v_fmac_f32_dpp v15, v31, v35 row_newbcast:2 row_mask:0xf bank_mask:0xf bound_ctrl:1
	v_fmac_f32_dpp v14, v31, v35 row_newbcast:3 row_mask:0xf bank_mask:0xf bound_ctrl:1
	v_fmac_f32_dpp v13, v31, v35 row_newbcast:4 row_mask:0xf bank_mask:0xf bound_ctrl:1
	v_fmac_f32_dpp v12, v31, v35 row_newbcast:5 row_mask:0xf bank_mask:0xf bound_ctrl:1
	v_fmac_f32_dpp v11, v31, v35 row_newbcast:6 row_mask:0xf bank_mask:0xf bound_ctrl:1
	v_fmac_f32_dpp v10, v31, v35 row_newbcast:7 row_mask:0xf bank_mask:0xf bound_ctrl:1
	v_fmac_f32_dpp v9, v31, v35 row_newbcast:8 row_mask:0xf bank_mask:0xf bound_ctrl:1
	v_fmac_f32_dpp v8, v31, v35 row_newbcast:9 row_mask:0xf bank_mask:0xf bound_ctrl:1
	v_fmac_f32_dpp v7, v31, v35 row_newbcast:10 row_mask:0xf bank_mask:0xf bound_ctrl:1
	v_fmac_f32_dpp v6, v31, v35 row_newbcast:11 row_mask:0xf bank_mask:0xf bound_ctrl:1
	v_fmac_f32_dpp v5, v31, v35 row_newbcast:12 row_mask:0xf bank_mask:0xf bound_ctrl:1
	v_fmac_f32_dpp v4, v31, v35 row_newbcast:13 row_mask:0xf bank_mask:0xf bound_ctrl:1
	v_fmac_f32_dpp v3, v31, v35 row_newbcast:14 row_mask:0xf bank_mask:0xf bound_ctrl:1
	v_fmac_f32_dpp v2, v31, v35 row_newbcast:15 row_mask:0xf bank_mask:0xf bound_ctrl:1
	s_nop 0
	v_add_f32 v37, v37, v38
	v_add_f32 v39, v39, v42
	s_nop 0
	v_add_f32 v37, v37, v39
	v_add_f32 v24, v24, v18
	v_add_f32 v25, v25, v23
	v_mfma_f32_16x16x4_f32 v[224:227], v228, v37, 0
	ds_write_b64 v22, v[24:25] offset:57344
	v_fmac_f32_dpp v17, v32, v34 row_newbcast:0 row_mask:0xf bank_mask:0xf bound_ctrl:1
	v_fmac_f32_dpp v16, v32, v34 row_newbcast:1 row_mask:0xf bank_mask:0xf bound_ctrl:1
	v_fmac_f32_dpp v15, v32, v34 row_newbcast:2 row_mask:0xf bank_mask:0xf bound_ctrl:1
	v_fmac_f32_dpp v14, v32, v34 row_newbcast:3 row_mask:0xf bank_mask:0xf bound_ctrl:1
	v_fmac_f32_dpp v13, v32, v34 row_newbcast:4 row_mask:0xf bank_mask:0xf bound_ctrl:1
	v_fmac_f32_dpp v12, v32, v34 row_newbcast:5 row_mask:0xf bank_mask:0xf bound_ctrl:1
	v_fmac_f32_dpp v11, v32, v34 row_newbcast:6 row_mask:0xf bank_mask:0xf bound_ctrl:1
	v_fmac_f32_dpp v10, v32, v34 row_newbcast:7 row_mask:0xf bank_mask:0xf bound_ctrl:1
	v_fmac_f32_dpp v9, v32, v34 row_newbcast:8 row_mask:0xf bank_mask:0xf bound_ctrl:1
	v_fmac_f32_dpp v8, v32, v34 row_newbcast:9 row_mask:0xf bank_mask:0xf bound_ctrl:1
	v_fmac_f32_dpp v7, v32, v34 row_newbcast:10 row_mask:0xf bank_mask:0xf bound_ctrl:1
	v_fmac_f32_dpp v6, v32, v34 row_newbcast:11 row_mask:0xf bank_mask:0xf bound_ctrl:1
	v_fmac_f32_dpp v5, v32, v34 row_newbcast:12 row_mask:0xf bank_mask:0xf bound_ctrl:1
	v_fmac_f32_dpp v4, v32, v34 row_newbcast:13 row_mask:0xf bank_mask:0xf bound_ctrl:1
	v_fmac_f32_dpp v3, v32, v34 row_newbcast:14 row_mask:0xf bank_mask:0xf bound_ctrl:1
	v_fmac_f32_dpp v2, v32, v34 row_newbcast:15 row_mask:0xf bank_mask:0xf bound_ctrl:1
	v_mul_f32_dpp v24, v33, v17 row_newbcast:0 row_mask:0xf bank_mask:0xf bound_ctrl:1
	v_mul_f32_dpp v18, v33, v16 row_newbcast:1 row_mask:0xf bank_mask:0xf bound_ctrl:1
	v_mul_f32_dpp v25, v33, v15 row_newbcast:2 row_mask:0xf bank_mask:0xf bound_ctrl:1
	v_mul_f32_dpp v23, v33, v14 row_newbcast:3 row_mask:0xf bank_mask:0xf bound_ctrl:1
	v_fmac_f32_dpp v24, v33, v13 row_newbcast:4 row_mask:0xf bank_mask:0xf bound_ctrl:1
	v_fmac_f32_dpp v18, v33, v12 row_newbcast:5 row_mask:0xf bank_mask:0xf bound_ctrl:1
	v_fmac_f32_dpp v25, v33, v11 row_newbcast:6 row_mask:0xf bank_mask:0xf bound_ctrl:1
	v_fmac_f32_dpp v23, v33, v10 row_newbcast:7 row_mask:0xf bank_mask:0xf bound_ctrl:1
	s_nop 0
	v_fmac_f32_dpp v24, v33, v9 row_newbcast:8 row_mask:0xf bank_mask:0xf bound_ctrl:1
	v_fmac_f32_dpp v18, v33, v8 row_newbcast:9 row_mask:0xf bank_mask:0xf bound_ctrl:1
	v_fmac_f32_dpp v25, v33, v7 row_newbcast:10 row_mask:0xf bank_mask:0xf bound_ctrl:1
	v_fmac_f32_dpp v23, v33, v6 row_newbcast:11 row_mask:0xf bank_mask:0xf bound_ctrl:1
	s_nop 0
	v_fmac_f32_dpp v24, v33, v5 row_newbcast:12 row_mask:0xf bank_mask:0xf bound_ctrl:1
	v_fmac_f32_dpp v18, v33, v4 row_newbcast:13 row_mask:0xf bank_mask:0xf bound_ctrl:1
	v_fmac_f32_dpp v25, v33, v3 row_newbcast:14 row_mask:0xf bank_mask:0xf bound_ctrl:1
	v_fmac_f32_dpp v23, v33, v2 row_newbcast:15 row_mask:0xf bank_mask:0xf bound_ctrl:1
	s_waitcnt lgkmcnt(0)
	v_mov_b32_e32 v37, v224
	ds_read_b32 v38, v19 offset:22272
	ds_read2st64_b32 v[30:31], v21 offset0:23 offset1:39
	ds_read2st64_b32 v[32:33], v21 offset0:55 offset1:71
	v_mul_f32_dpp v39, v26, v17 row_newbcast:0 row_mask:0xf bank_mask:0xf bound_ctrl:1
	v_mul_f32_dpp v40, v26, v16 row_newbcast:1 row_mask:0xf bank_mask:0xf bound_ctrl:1
	v_mul_f32_dpp v41, v26, v15 row_newbcast:2 row_mask:0xf bank_mask:0xf bound_ctrl:1
	v_mul_f32_dpp v42, v26, v14 row_newbcast:3 row_mask:0xf bank_mask:0xf bound_ctrl:1
	v_fmac_f32_e32 v37, s90, v35
	v_fmac_f32_dpp v39, v26, v13 row_newbcast:4 row_mask:0xf bank_mask:0xf bound_ctrl:1
	v_fmac_f32_dpp v40, v26, v12 row_newbcast:5 row_mask:0xf bank_mask:0xf bound_ctrl:1
	v_fmac_f32_dpp v41, v26, v11 row_newbcast:6 row_mask:0xf bank_mask:0xf bound_ctrl:1
	v_fmac_f32_dpp v42, v26, v10 row_newbcast:7 row_mask:0xf bank_mask:0xf bound_ctrl:1
	v_fmac_f32_e32 v37, s89, v34
	v_fmac_f32_dpp v39, v26, v9 row_newbcast:8 row_mask:0xf bank_mask:0xf bound_ctrl:1
	v_fmac_f32_dpp v40, v26, v8 row_newbcast:9 row_mask:0xf bank_mask:0xf bound_ctrl:1
	v_fmac_f32_dpp v41, v26, v7 row_newbcast:10 row_mask:0xf bank_mask:0xf bound_ctrl:1
	v_fmac_f32_dpp v42, v26, v6 row_newbcast:11 row_mask:0xf bank_mask:0xf bound_ctrl:1
	s_nop 0
	v_fmac_f32_dpp v39, v26, v5 row_newbcast:12 row_mask:0xf bank_mask:0xf bound_ctrl:1
	v_fmac_f32_dpp v40, v26, v4 row_newbcast:13 row_mask:0xf bank_mask:0xf bound_ctrl:1
	v_fmac_f32_dpp v41, v26, v3 row_newbcast:14 row_mask:0xf bank_mask:0xf bound_ctrl:1
	v_fmac_f32_dpp v42, v26, v2 row_newbcast:15 row_mask:0xf bank_mask:0xf bound_ctrl:1
	v_fmac_f32_dpp v17, v27, v37 row_newbcast:0 row_mask:0xf bank_mask:0xf bound_ctrl:1
	v_fmac_f32_dpp v16, v27, v37 row_newbcast:1 row_mask:0xf bank_mask:0xf bound_ctrl:1
	v_fmac_f32_dpp v15, v27, v37 row_newbcast:2 row_mask:0xf bank_mask:0xf bound_ctrl:1
	v_fmac_f32_dpp v14, v27, v37 row_newbcast:3 row_mask:0xf bank_mask:0xf bound_ctrl:1
	v_fmac_f32_dpp v13, v27, v37 row_newbcast:4 row_mask:0xf bank_mask:0xf bound_ctrl:1
	v_fmac_f32_dpp v12, v27, v37 row_newbcast:5 row_mask:0xf bank_mask:0xf bound_ctrl:1
	v_fmac_f32_dpp v11, v27, v37 row_newbcast:6 row_mask:0xf bank_mask:0xf bound_ctrl:1
	v_fmac_f32_dpp v10, v27, v37 row_newbcast:7 row_mask:0xf bank_mask:0xf bound_ctrl:1
	v_fmac_f32_dpp v9, v27, v37 row_newbcast:8 row_mask:0xf bank_mask:0xf bound_ctrl:1
	v_fmac_f32_dpp v8, v27, v37 row_newbcast:9 row_mask:0xf bank_mask:0xf bound_ctrl:1
	v_fmac_f32_dpp v7, v27, v37 row_newbcast:10 row_mask:0xf bank_mask:0xf bound_ctrl:1
	v_fmac_f32_dpp v6, v27, v37 row_newbcast:11 row_mask:0xf bank_mask:0xf bound_ctrl:1
	v_fmac_f32_dpp v5, v27, v37 row_newbcast:12 row_mask:0xf bank_mask:0xf bound_ctrl:1
	v_fmac_f32_dpp v4, v27, v37 row_newbcast:13 row_mask:0xf bank_mask:0xf bound_ctrl:1
	v_fmac_f32_dpp v3, v27, v37 row_newbcast:14 row_mask:0xf bank_mask:0xf bound_ctrl:1
	v_fmac_f32_dpp v2, v27, v37 row_newbcast:15 row_mask:0xf bank_mask:0xf bound_ctrl:1
	s_nop 0
	v_add_f32 v39, v39, v40
	v_add_f32 v41, v41, v42
	s_nop 0
	v_add_f32 v39, v39, v41
	v_add_f32 v24, v24, v18
	v_add_f32 v25, v25, v23
	v_mfma_f32_16x16x4_f32 v[224:227], v228, v39, 0
	ds_write_b64 v22, v[24:25] offset:59392
	v_fmac_f32_dpp v17, v28, v36 row_newbcast:0 row_mask:0xf bank_mask:0xf bound_ctrl:1
	v_fmac_f32_dpp v16, v28, v36 row_newbcast:1 row_mask:0xf bank_mask:0xf bound_ctrl:1
	v_fmac_f32_dpp v15, v28, v36 row_newbcast:2 row_mask:0xf bank_mask:0xf bound_ctrl:1
	v_fmac_f32_dpp v14, v28, v36 row_newbcast:3 row_mask:0xf bank_mask:0xf bound_ctrl:1
	v_fmac_f32_dpp v13, v28, v36 row_newbcast:4 row_mask:0xf bank_mask:0xf bound_ctrl:1
	v_fmac_f32_dpp v12, v28, v36 row_newbcast:5 row_mask:0xf bank_mask:0xf bound_ctrl:1
	v_fmac_f32_dpp v11, v28, v36 row_newbcast:6 row_mask:0xf bank_mask:0xf bound_ctrl:1
	v_fmac_f32_dpp v10, v28, v36 row_newbcast:7 row_mask:0xf bank_mask:0xf bound_ctrl:1
	v_fmac_f32_dpp v9, v28, v36 row_newbcast:8 row_mask:0xf bank_mask:0xf bound_ctrl:1
	v_fmac_f32_dpp v8, v28, v36 row_newbcast:9 row_mask:0xf bank_mask:0xf bound_ctrl:1
	v_fmac_f32_dpp v7, v28, v36 row_newbcast:10 row_mask:0xf bank_mask:0xf bound_ctrl:1
	v_fmac_f32_dpp v6, v28, v36 row_newbcast:11 row_mask:0xf bank_mask:0xf bound_ctrl:1
	v_fmac_f32_dpp v5, v28, v36 row_newbcast:12 row_mask:0xf bank_mask:0xf bound_ctrl:1
	v_fmac_f32_dpp v4, v28, v36 row_newbcast:13 row_mask:0xf bank_mask:0xf bound_ctrl:1
	v_fmac_f32_dpp v3, v28, v36 row_newbcast:14 row_mask:0xf bank_mask:0xf bound_ctrl:1
	v_fmac_f32_dpp v2, v28, v36 row_newbcast:15 row_mask:0xf bank_mask:0xf bound_ctrl:1
	v_mul_f32_dpp v24, v29, v17 row_newbcast:0 row_mask:0xf bank_mask:0xf bound_ctrl:1
	v_mul_f32_dpp v18, v29, v16 row_newbcast:1 row_mask:0xf bank_mask:0xf bound_ctrl:1
	v_mul_f32_dpp v25, v29, v15 row_newbcast:2 row_mask:0xf bank_mask:0xf bound_ctrl:1
	v_mul_f32_dpp v23, v29, v14 row_newbcast:3 row_mask:0xf bank_mask:0xf bound_ctrl:1
	v_fmac_f32_dpp v24, v29, v13 row_newbcast:4 row_mask:0xf bank_mask:0xf bound_ctrl:1
	v_fmac_f32_dpp v18, v29, v12 row_newbcast:5 row_mask:0xf bank_mask:0xf bound_ctrl:1
	v_fmac_f32_dpp v25, v29, v11 row_newbcast:6 row_mask:0xf bank_mask:0xf bound_ctrl:1
	v_fmac_f32_dpp v23, v29, v10 row_newbcast:7 row_mask:0xf bank_mask:0xf bound_ctrl:1
	s_nop 0
	v_fmac_f32_dpp v24, v29, v9 row_newbcast:8 row_mask:0xf bank_mask:0xf bound_ctrl:1
	v_fmac_f32_dpp v18, v29, v8 row_newbcast:9 row_mask:0xf bank_mask:0xf bound_ctrl:1
	v_fmac_f32_dpp v25, v29, v7 row_newbcast:10 row_mask:0xf bank_mask:0xf bound_ctrl:1
	v_fmac_f32_dpp v23, v29, v6 row_newbcast:11 row_mask:0xf bank_mask:0xf bound_ctrl:1
	s_nop 0
	v_fmac_f32_dpp v24, v29, v5 row_newbcast:12 row_mask:0xf bank_mask:0xf bound_ctrl:1
	v_fmac_f32_dpp v18, v29, v4 row_newbcast:13 row_mask:0xf bank_mask:0xf bound_ctrl:1
	v_fmac_f32_dpp v25, v29, v3 row_newbcast:14 row_mask:0xf bank_mask:0xf bound_ctrl:1
	v_fmac_f32_dpp v23, v29, v2 row_newbcast:15 row_mask:0xf bank_mask:0xf bound_ctrl:1
	s_waitcnt lgkmcnt(0)
	v_mov_b32_e32 v39, v224
	ds_read_b32 v34, v19 offset:22528
	ds_read2st64_b32 v[26:27], v21 offset0:24 offset1:40
	ds_read2st64_b32 v[28:29], v21 offset0:56 offset1:72
	v_mul_f32_dpp v35, v30, v17 row_newbcast:0 row_mask:0xf bank_mask:0xf bound_ctrl:1
	v_mul_f32_dpp v40, v30, v16 row_newbcast:1 row_mask:0xf bank_mask:0xf bound_ctrl:1
	v_mul_f32_dpp v41, v30, v15 row_newbcast:2 row_mask:0xf bank_mask:0xf bound_ctrl:1
	v_mul_f32_dpp v42, v30, v14 row_newbcast:3 row_mask:0xf bank_mask:0xf bound_ctrl:1
	v_fmac_f32_e32 v39, s88, v37
	v_fmac_f32_dpp v35, v30, v13 row_newbcast:4 row_mask:0xf bank_mask:0xf bound_ctrl:1
	v_fmac_f32_dpp v40, v30, v12 row_newbcast:5 row_mask:0xf bank_mask:0xf bound_ctrl:1
	v_fmac_f32_dpp v41, v30, v11 row_newbcast:6 row_mask:0xf bank_mask:0xf bound_ctrl:1
	v_fmac_f32_dpp v42, v30, v10 row_newbcast:7 row_mask:0xf bank_mask:0xf bound_ctrl:1
	v_fmac_f32_e32 v39, s83, v36
	v_fmac_f32_dpp v35, v30, v9 row_newbcast:8 row_mask:0xf bank_mask:0xf bound_ctrl:1
	v_fmac_f32_dpp v40, v30, v8 row_newbcast:9 row_mask:0xf bank_mask:0xf bound_ctrl:1
	v_fmac_f32_dpp v41, v30, v7 row_newbcast:10 row_mask:0xf bank_mask:0xf bound_ctrl:1
	v_fmac_f32_dpp v42, v30, v6 row_newbcast:11 row_mask:0xf bank_mask:0xf bound_ctrl:1
	s_nop 0
	v_fmac_f32_dpp v35, v30, v5 row_newbcast:12 row_mask:0xf bank_mask:0xf bound_ctrl:1
	v_fmac_f32_dpp v40, v30, v4 row_newbcast:13 row_mask:0xf bank_mask:0xf bound_ctrl:1
	v_fmac_f32_dpp v41, v30, v3 row_newbcast:14 row_mask:0xf bank_mask:0xf bound_ctrl:1
	v_fmac_f32_dpp v42, v30, v2 row_newbcast:15 row_mask:0xf bank_mask:0xf bound_ctrl:1
	v_fmac_f32_dpp v17, v31, v39 row_newbcast:0 row_mask:0xf bank_mask:0xf bound_ctrl:1
	v_fmac_f32_dpp v16, v31, v39 row_newbcast:1 row_mask:0xf bank_mask:0xf bound_ctrl:1
	v_fmac_f32_dpp v15, v31, v39 row_newbcast:2 row_mask:0xf bank_mask:0xf bound_ctrl:1
	v_fmac_f32_dpp v14, v31, v39 row_newbcast:3 row_mask:0xf bank_mask:0xf bound_ctrl:1
	v_fmac_f32_dpp v13, v31, v39 row_newbcast:4 row_mask:0xf bank_mask:0xf bound_ctrl:1
	v_fmac_f32_dpp v12, v31, v39 row_newbcast:5 row_mask:0xf bank_mask:0xf bound_ctrl:1
	v_fmac_f32_dpp v11, v31, v39 row_newbcast:6 row_mask:0xf bank_mask:0xf bound_ctrl:1
	v_fmac_f32_dpp v10, v31, v39 row_newbcast:7 row_mask:0xf bank_mask:0xf bound_ctrl:1
	v_fmac_f32_dpp v9, v31, v39 row_newbcast:8 row_mask:0xf bank_mask:0xf bound_ctrl:1
	v_fmac_f32_dpp v8, v31, v39 row_newbcast:9 row_mask:0xf bank_mask:0xf bound_ctrl:1
	v_fmac_f32_dpp v7, v31, v39 row_newbcast:10 row_mask:0xf bank_mask:0xf bound_ctrl:1
	v_fmac_f32_dpp v6, v31, v39 row_newbcast:11 row_mask:0xf bank_mask:0xf bound_ctrl:1
	v_fmac_f32_dpp v5, v31, v39 row_newbcast:12 row_mask:0xf bank_mask:0xf bound_ctrl:1
	v_fmac_f32_dpp v4, v31, v39 row_newbcast:13 row_mask:0xf bank_mask:0xf bound_ctrl:1
	v_fmac_f32_dpp v3, v31, v39 row_newbcast:14 row_mask:0xf bank_mask:0xf bound_ctrl:1
	v_fmac_f32_dpp v2, v31, v39 row_newbcast:15 row_mask:0xf bank_mask:0xf bound_ctrl:1
	s_nop 0
	v_add_f32 v35, v35, v40
	v_add_f32 v41, v41, v42
	s_nop 0
	v_add_f32 v35, v35, v41
	v_add_f32 v24, v24, v18
	v_add_f32 v25, v25, v23
	v_mfma_f32_16x16x4_f32 v[224:227], v228, v35, 0
	ds_write_b64 v22, v[24:25] offset:61440
	v_fmac_f32_dpp v17, v32, v38 row_newbcast:0 row_mask:0xf bank_mask:0xf bound_ctrl:1
	v_fmac_f32_dpp v16, v32, v38 row_newbcast:1 row_mask:0xf bank_mask:0xf bound_ctrl:1
	v_fmac_f32_dpp v15, v32, v38 row_newbcast:2 row_mask:0xf bank_mask:0xf bound_ctrl:1
	v_fmac_f32_dpp v14, v32, v38 row_newbcast:3 row_mask:0xf bank_mask:0xf bound_ctrl:1
	v_fmac_f32_dpp v13, v32, v38 row_newbcast:4 row_mask:0xf bank_mask:0xf bound_ctrl:1
	v_fmac_f32_dpp v12, v32, v38 row_newbcast:5 row_mask:0xf bank_mask:0xf bound_ctrl:1
	v_fmac_f32_dpp v11, v32, v38 row_newbcast:6 row_mask:0xf bank_mask:0xf bound_ctrl:1
	v_fmac_f32_dpp v10, v32, v38 row_newbcast:7 row_mask:0xf bank_mask:0xf bound_ctrl:1
	v_fmac_f32_dpp v9, v32, v38 row_newbcast:8 row_mask:0xf bank_mask:0xf bound_ctrl:1
	v_fmac_f32_dpp v8, v32, v38 row_newbcast:9 row_mask:0xf bank_mask:0xf bound_ctrl:1
	v_fmac_f32_dpp v7, v32, v38 row_newbcast:10 row_mask:0xf bank_mask:0xf bound_ctrl:1
	v_fmac_f32_dpp v6, v32, v38 row_newbcast:11 row_mask:0xf bank_mask:0xf bound_ctrl:1
	v_fmac_f32_dpp v5, v32, v38 row_newbcast:12 row_mask:0xf bank_mask:0xf bound_ctrl:1
	v_fmac_f32_dpp v4, v32, v38 row_newbcast:13 row_mask:0xf bank_mask:0xf bound_ctrl:1
	v_fmac_f32_dpp v3, v32, v38 row_newbcast:14 row_mask:0xf bank_mask:0xf bound_ctrl:1
	v_fmac_f32_dpp v2, v32, v38 row_newbcast:15 row_mask:0xf bank_mask:0xf bound_ctrl:1
	v_mul_f32_dpp v24, v33, v17 row_newbcast:0 row_mask:0xf bank_mask:0xf bound_ctrl:1
	v_mul_f32_dpp v18, v33, v16 row_newbcast:1 row_mask:0xf bank_mask:0xf bound_ctrl:1
	v_mul_f32_dpp v25, v33, v15 row_newbcast:2 row_mask:0xf bank_mask:0xf bound_ctrl:1
	v_mul_f32_dpp v23, v33, v14 row_newbcast:3 row_mask:0xf bank_mask:0xf bound_ctrl:1
	v_fmac_f32_dpp v24, v33, v13 row_newbcast:4 row_mask:0xf bank_mask:0xf bound_ctrl:1
	v_fmac_f32_dpp v18, v33, v12 row_newbcast:5 row_mask:0xf bank_mask:0xf bound_ctrl:1
	v_fmac_f32_dpp v25, v33, v11 row_newbcast:6 row_mask:0xf bank_mask:0xf bound_ctrl:1
	v_fmac_f32_dpp v23, v33, v10 row_newbcast:7 row_mask:0xf bank_mask:0xf bound_ctrl:1
	s_nop 0
	v_fmac_f32_dpp v24, v33, v9 row_newbcast:8 row_mask:0xf bank_mask:0xf bound_ctrl:1
	v_fmac_f32_dpp v18, v33, v8 row_newbcast:9 row_mask:0xf bank_mask:0xf bound_ctrl:1
	v_fmac_f32_dpp v25, v33, v7 row_newbcast:10 row_mask:0xf bank_mask:0xf bound_ctrl:1
	v_fmac_f32_dpp v23, v33, v6 row_newbcast:11 row_mask:0xf bank_mask:0xf bound_ctrl:1
	s_nop 0
	v_fmac_f32_dpp v24, v33, v5 row_newbcast:12 row_mask:0xf bank_mask:0xf bound_ctrl:1
	v_fmac_f32_dpp v18, v33, v4 row_newbcast:13 row_mask:0xf bank_mask:0xf bound_ctrl:1
	v_fmac_f32_dpp v25, v33, v3 row_newbcast:14 row_mask:0xf bank_mask:0xf bound_ctrl:1
	v_fmac_f32_dpp v23, v33, v2 row_newbcast:15 row_mask:0xf bank_mask:0xf bound_ctrl:1
	s_waitcnt lgkmcnt(0)
	v_mov_b32_e32 v35, v224
	ds_read_b32 v36, v19 offset:22784
	ds_read2st64_b32 v[30:31], v21 offset0:25 offset1:41
	ds_read2st64_b32 v[32:33], v21 offset0:57 offset1:73
	v_mul_f32_dpp v37, v26, v17 row_newbcast:0 row_mask:0xf bank_mask:0xf bound_ctrl:1
	v_mul_f32_dpp v40, v26, v16 row_newbcast:1 row_mask:0xf bank_mask:0xf bound_ctrl:1
	v_mul_f32_dpp v41, v26, v15 row_newbcast:2 row_mask:0xf bank_mask:0xf bound_ctrl:1
	v_mul_f32_dpp v42, v26, v14 row_newbcast:3 row_mask:0xf bank_mask:0xf bound_ctrl:1
	v_fmac_f32_e32 v35, s82, v39
	v_fmac_f32_dpp v37, v26, v13 row_newbcast:4 row_mask:0xf bank_mask:0xf bound_ctrl:1
	v_fmac_f32_dpp v40, v26, v12 row_newbcast:5 row_mask:0xf bank_mask:0xf bound_ctrl:1
	v_fmac_f32_dpp v41, v26, v11 row_newbcast:6 row_mask:0xf bank_mask:0xf bound_ctrl:1
	v_fmac_f32_dpp v42, v26, v10 row_newbcast:7 row_mask:0xf bank_mask:0xf bound_ctrl:1
	v_fmac_f32_e32 v35, s81, v38
	v_fmac_f32_dpp v37, v26, v9 row_newbcast:8 row_mask:0xf bank_mask:0xf bound_ctrl:1
	v_fmac_f32_dpp v40, v26, v8 row_newbcast:9 row_mask:0xf bank_mask:0xf bound_ctrl:1
	v_fmac_f32_dpp v41, v26, v7 row_newbcast:10 row_mask:0xf bank_mask:0xf bound_ctrl:1
	v_fmac_f32_dpp v42, v26, v6 row_newbcast:11 row_mask:0xf bank_mask:0xf bound_ctrl:1
	s_nop 0
	v_fmac_f32_dpp v37, v26, v5 row_newbcast:12 row_mask:0xf bank_mask:0xf bound_ctrl:1
	v_fmac_f32_dpp v40, v26, v4 row_newbcast:13 row_mask:0xf bank_mask:0xf bound_ctrl:1
	v_fmac_f32_dpp v41, v26, v3 row_newbcast:14 row_mask:0xf bank_mask:0xf bound_ctrl:1
	v_fmac_f32_dpp v42, v26, v2 row_newbcast:15 row_mask:0xf bank_mask:0xf bound_ctrl:1
	v_fmac_f32_dpp v17, v27, v35 row_newbcast:0 row_mask:0xf bank_mask:0xf bound_ctrl:1
	v_fmac_f32_dpp v16, v27, v35 row_newbcast:1 row_mask:0xf bank_mask:0xf bound_ctrl:1
	v_fmac_f32_dpp v15, v27, v35 row_newbcast:2 row_mask:0xf bank_mask:0xf bound_ctrl:1
	v_fmac_f32_dpp v14, v27, v35 row_newbcast:3 row_mask:0xf bank_mask:0xf bound_ctrl:1
	v_fmac_f32_dpp v13, v27, v35 row_newbcast:4 row_mask:0xf bank_mask:0xf bound_ctrl:1
	v_fmac_f32_dpp v12, v27, v35 row_newbcast:5 row_mask:0xf bank_mask:0xf bound_ctrl:1
	v_fmac_f32_dpp v11, v27, v35 row_newbcast:6 row_mask:0xf bank_mask:0xf bound_ctrl:1
	v_fmac_f32_dpp v10, v27, v35 row_newbcast:7 row_mask:0xf bank_mask:0xf bound_ctrl:1
	v_fmac_f32_dpp v9, v27, v35 row_newbcast:8 row_mask:0xf bank_mask:0xf bound_ctrl:1
	v_fmac_f32_dpp v8, v27, v35 row_newbcast:9 row_mask:0xf bank_mask:0xf bound_ctrl:1
	v_fmac_f32_dpp v7, v27, v35 row_newbcast:10 row_mask:0xf bank_mask:0xf bound_ctrl:1
	v_fmac_f32_dpp v6, v27, v35 row_newbcast:11 row_mask:0xf bank_mask:0xf bound_ctrl:1
	v_fmac_f32_dpp v5, v27, v35 row_newbcast:12 row_mask:0xf bank_mask:0xf bound_ctrl:1
	v_fmac_f32_dpp v4, v27, v35 row_newbcast:13 row_mask:0xf bank_mask:0xf bound_ctrl:1
	v_fmac_f32_dpp v3, v27, v35 row_newbcast:14 row_mask:0xf bank_mask:0xf bound_ctrl:1
	v_fmac_f32_dpp v2, v27, v35 row_newbcast:15 row_mask:0xf bank_mask:0xf bound_ctrl:1
	s_nop 0
	v_add_f32 v37, v37, v40
	v_add_f32 v41, v41, v42
	s_nop 0
	v_add_f32 v37, v37, v41
	v_add_f32 v24, v24, v18
	s_nop 0
	v_mfma_f32_16x16x4_f32 v[224:227], v228, v37, 0
	v_add_f32 v25, v25, v23
	ds_write_b64 v22, v[24:25] offset:63488
	v_fmac_f32_dpp v17, v28, v34 row_newbcast:0 row_mask:0xf bank_mask:0xf bound_ctrl:1
	v_fmac_f32_dpp v16, v28, v34 row_newbcast:1 row_mask:0xf bank_mask:0xf bound_ctrl:1
	v_fmac_f32_dpp v15, v28, v34 row_newbcast:2 row_mask:0xf bank_mask:0xf bound_ctrl:1
	v_fmac_f32_dpp v14, v28, v34 row_newbcast:3 row_mask:0xf bank_mask:0xf bound_ctrl:1
	v_fmac_f32_dpp v13, v28, v34 row_newbcast:4 row_mask:0xf bank_mask:0xf bound_ctrl:1
	v_fmac_f32_dpp v12, v28, v34 row_newbcast:5 row_mask:0xf bank_mask:0xf bound_ctrl:1
	v_fmac_f32_dpp v11, v28, v34 row_newbcast:6 row_mask:0xf bank_mask:0xf bound_ctrl:1
	v_fmac_f32_dpp v10, v28, v34 row_newbcast:7 row_mask:0xf bank_mask:0xf bound_ctrl:1
	v_fmac_f32_dpp v9, v28, v34 row_newbcast:8 row_mask:0xf bank_mask:0xf bound_ctrl:1
	v_fmac_f32_dpp v8, v28, v34 row_newbcast:9 row_mask:0xf bank_mask:0xf bound_ctrl:1
	v_fmac_f32_dpp v7, v28, v34 row_newbcast:10 row_mask:0xf bank_mask:0xf bound_ctrl:1
	v_fmac_f32_dpp v6, v28, v34 row_newbcast:11 row_mask:0xf bank_mask:0xf bound_ctrl:1
	v_fmac_f32_dpp v5, v28, v34 row_newbcast:12 row_mask:0xf bank_mask:0xf bound_ctrl:1
	v_fmac_f32_dpp v4, v28, v34 row_newbcast:13 row_mask:0xf bank_mask:0xf bound_ctrl:1
	v_fmac_f32_dpp v3, v28, v34 row_newbcast:14 row_mask:0xf bank_mask:0xf bound_ctrl:1
	v_fmac_f32_dpp v2, v28, v34 row_newbcast:15 row_mask:0xf bank_mask:0xf bound_ctrl:1
	v_mul_f32_dpp v22, v29, v17 row_newbcast:0 row_mask:0xf bank_mask:0xf bound_ctrl:1
	v_mul_f32_dpp v18, v29, v16 row_newbcast:1 row_mask:0xf bank_mask:0xf bound_ctrl:1
	v_mul_f32_dpp v23, v29, v15 row_newbcast:2 row_mask:0xf bank_mask:0xf bound_ctrl:1
	v_mul_f32_dpp v28, v29, v14 row_newbcast:3 row_mask:0xf bank_mask:0xf bound_ctrl:1
	v_fmac_f32_dpp v22, v29, v13 row_newbcast:4 row_mask:0xf bank_mask:0xf bound_ctrl:1
	v_fmac_f32_dpp v18, v29, v12 row_newbcast:5 row_mask:0xf bank_mask:0xf bound_ctrl:1
	v_fmac_f32_dpp v23, v29, v11 row_newbcast:6 row_mask:0xf bank_mask:0xf bound_ctrl:1
	v_fmac_f32_dpp v28, v29, v10 row_newbcast:7 row_mask:0xf bank_mask:0xf bound_ctrl:1
	s_nop 0
	v_fmac_f32_dpp v22, v29, v9 row_newbcast:8 row_mask:0xf bank_mask:0xf bound_ctrl:1
	v_fmac_f32_dpp v18, v29, v8 row_newbcast:9 row_mask:0xf bank_mask:0xf bound_ctrl:1
	v_fmac_f32_dpp v23, v29, v7 row_newbcast:10 row_mask:0xf bank_mask:0xf bound_ctrl:1
	v_fmac_f32_dpp v28, v29, v6 row_newbcast:11 row_mask:0xf bank_mask:0xf bound_ctrl:1
	s_nop 0
	v_fmac_f32_dpp v22, v29, v5 row_newbcast:12 row_mask:0xf bank_mask:0xf bound_ctrl:1
	v_fmac_f32_dpp v18, v29, v4 row_newbcast:13 row_mask:0xf bank_mask:0xf bound_ctrl:1
	v_fmac_f32_dpp v23, v29, v3 row_newbcast:14 row_mask:0xf bank_mask:0xf bound_ctrl:1
	v_fmac_f32_dpp v28, v29, v2 row_newbcast:15 row_mask:0xf bank_mask:0xf bound_ctrl:1
	s_waitcnt lgkmcnt(0)
	v_mov_b32_e32 v37, v224
	ds_read_b32 v38, v19 offset:23040
	ds_read2st64_b32 v[24:25], v21 offset0:26 offset1:42
	ds_read2st64_b32 v[26:27], v21 offset0:58 offset1:74
	v_mul_f32_dpp v39, v30, v17 row_newbcast:0 row_mask:0xf bank_mask:0xf bound_ctrl:1
	v_mul_f32_dpp v29, v30, v16 row_newbcast:1 row_mask:0xf bank_mask:0xf bound_ctrl:1
	v_mul_f32_dpp v40, v30, v15 row_newbcast:2 row_mask:0xf bank_mask:0xf bound_ctrl:1
	v_mul_f32_dpp v41, v30, v14 row_newbcast:3 row_mask:0xf bank_mask:0xf bound_ctrl:1
	v_fmac_f32_e32 v37, s80, v35
	v_fmac_f32_dpp v39, v30, v13 row_newbcast:4 row_mask:0xf bank_mask:0xf bound_ctrl:1
	v_fmac_f32_dpp v29, v30, v12 row_newbcast:5 row_mask:0xf bank_mask:0xf bound_ctrl:1
	v_fmac_f32_dpp v40, v30, v11 row_newbcast:6 row_mask:0xf bank_mask:0xf bound_ctrl:1
	v_fmac_f32_dpp v41, v30, v10 row_newbcast:7 row_mask:0xf bank_mask:0xf bound_ctrl:1
	v_fmac_f32_e32 v37, s79, v34
	v_fmac_f32_dpp v39, v30, v9 row_newbcast:8 row_mask:0xf bank_mask:0xf bound_ctrl:1
	v_fmac_f32_dpp v29, v30, v8 row_newbcast:9 row_mask:0xf bank_mask:0xf bound_ctrl:1
	v_fmac_f32_dpp v40, v30, v7 row_newbcast:10 row_mask:0xf bank_mask:0xf bound_ctrl:1
	v_fmac_f32_dpp v41, v30, v6 row_newbcast:11 row_mask:0xf bank_mask:0xf bound_ctrl:1
	s_nop 0
	v_fmac_f32_dpp v39, v30, v5 row_newbcast:12 row_mask:0xf bank_mask:0xf bound_ctrl:1
	v_fmac_f32_dpp v29, v30, v4 row_newbcast:13 row_mask:0xf bank_mask:0xf bound_ctrl:1
	v_fmac_f32_dpp v40, v30, v3 row_newbcast:14 row_mask:0xf bank_mask:0xf bound_ctrl:1
	v_fmac_f32_dpp v41, v30, v2 row_newbcast:15 row_mask:0xf bank_mask:0xf bound_ctrl:1
	v_fmac_f32_dpp v17, v31, v37 row_newbcast:0 row_mask:0xf bank_mask:0xf bound_ctrl:1
	v_fmac_f32_dpp v16, v31, v37 row_newbcast:1 row_mask:0xf bank_mask:0xf bound_ctrl:1
	v_fmac_f32_dpp v15, v31, v37 row_newbcast:2 row_mask:0xf bank_mask:0xf bound_ctrl:1
	v_fmac_f32_dpp v14, v31, v37 row_newbcast:3 row_mask:0xf bank_mask:0xf bound_ctrl:1
	v_fmac_f32_dpp v13, v31, v37 row_newbcast:4 row_mask:0xf bank_mask:0xf bound_ctrl:1
	v_fmac_f32_dpp v12, v31, v37 row_newbcast:5 row_mask:0xf bank_mask:0xf bound_ctrl:1
	v_fmac_f32_dpp v11, v31, v37 row_newbcast:6 row_mask:0xf bank_mask:0xf bound_ctrl:1
	v_fmac_f32_dpp v10, v31, v37 row_newbcast:7 row_mask:0xf bank_mask:0xf bound_ctrl:1
	v_fmac_f32_dpp v9, v31, v37 row_newbcast:8 row_mask:0xf bank_mask:0xf bound_ctrl:1
	v_fmac_f32_dpp v8, v31, v37 row_newbcast:9 row_mask:0xf bank_mask:0xf bound_ctrl:1
	v_fmac_f32_dpp v7, v31, v37 row_newbcast:10 row_mask:0xf bank_mask:0xf bound_ctrl:1
	v_fmac_f32_dpp v6, v31, v37 row_newbcast:11 row_mask:0xf bank_mask:0xf bound_ctrl:1
	v_fmac_f32_dpp v5, v31, v37 row_newbcast:12 row_mask:0xf bank_mask:0xf bound_ctrl:1
	v_fmac_f32_dpp v4, v31, v37 row_newbcast:13 row_mask:0xf bank_mask:0xf bound_ctrl:1
	v_fmac_f32_dpp v3, v31, v37 row_newbcast:14 row_mask:0xf bank_mask:0xf bound_ctrl:1
	v_fmac_f32_dpp v2, v31, v37 row_newbcast:15 row_mask:0xf bank_mask:0xf bound_ctrl:1
	s_nop 0
	v_add_f32 v39, v39, v29
	v_add_f32 v40, v40, v41
	s_nop 0
	v_add_f32 v39, v39, v40
	v_add_f32 v22, v22, v18
	v_add_f32 v23, v23, v28
	v_mfma_f32_16x16x4_f32 v[224:227], v228, v39, 0
	ds_write_b64 v20, v[22:23] offset:16384
	v_fmac_f32_dpp v17, v32, v36 row_newbcast:0 row_mask:0xf bank_mask:0xf bound_ctrl:1
	v_fmac_f32_dpp v16, v32, v36 row_newbcast:1 row_mask:0xf bank_mask:0xf bound_ctrl:1
	v_fmac_f32_dpp v15, v32, v36 row_newbcast:2 row_mask:0xf bank_mask:0xf bound_ctrl:1
	v_fmac_f32_dpp v14, v32, v36 row_newbcast:3 row_mask:0xf bank_mask:0xf bound_ctrl:1
	v_fmac_f32_dpp v13, v32, v36 row_newbcast:4 row_mask:0xf bank_mask:0xf bound_ctrl:1
	v_fmac_f32_dpp v12, v32, v36 row_newbcast:5 row_mask:0xf bank_mask:0xf bound_ctrl:1
	v_fmac_f32_dpp v11, v32, v36 row_newbcast:6 row_mask:0xf bank_mask:0xf bound_ctrl:1
	v_fmac_f32_dpp v10, v32, v36 row_newbcast:7 row_mask:0xf bank_mask:0xf bound_ctrl:1
	v_fmac_f32_dpp v9, v32, v36 row_newbcast:8 row_mask:0xf bank_mask:0xf bound_ctrl:1
	v_fmac_f32_dpp v8, v32, v36 row_newbcast:9 row_mask:0xf bank_mask:0xf bound_ctrl:1
	v_fmac_f32_dpp v7, v32, v36 row_newbcast:10 row_mask:0xf bank_mask:0xf bound_ctrl:1
	v_fmac_f32_dpp v6, v32, v36 row_newbcast:11 row_mask:0xf bank_mask:0xf bound_ctrl:1
	v_fmac_f32_dpp v5, v32, v36 row_newbcast:12 row_mask:0xf bank_mask:0xf bound_ctrl:1
	v_fmac_f32_dpp v4, v32, v36 row_newbcast:13 row_mask:0xf bank_mask:0xf bound_ctrl:1
	v_fmac_f32_dpp v3, v32, v36 row_newbcast:14 row_mask:0xf bank_mask:0xf bound_ctrl:1
	v_fmac_f32_dpp v2, v32, v36 row_newbcast:15 row_mask:0xf bank_mask:0xf bound_ctrl:1
	v_mul_f32_dpp v22, v33, v17 row_newbcast:0 row_mask:0xf bank_mask:0xf bound_ctrl:1
	v_mul_f32_dpp v18, v33, v16 row_newbcast:1 row_mask:0xf bank_mask:0xf bound_ctrl:1
	v_mul_f32_dpp v23, v33, v15 row_newbcast:2 row_mask:0xf bank_mask:0xf bound_ctrl:1
	v_mul_f32_dpp v32, v33, v14 row_newbcast:3 row_mask:0xf bank_mask:0xf bound_ctrl:1
	v_fmac_f32_dpp v22, v33, v13 row_newbcast:4 row_mask:0xf bank_mask:0xf bound_ctrl:1
	v_fmac_f32_dpp v18, v33, v12 row_newbcast:5 row_mask:0xf bank_mask:0xf bound_ctrl:1
	v_fmac_f32_dpp v23, v33, v11 row_newbcast:6 row_mask:0xf bank_mask:0xf bound_ctrl:1
	v_fmac_f32_dpp v32, v33, v10 row_newbcast:7 row_mask:0xf bank_mask:0xf bound_ctrl:1
	s_nop 0
	v_fmac_f32_dpp v22, v33, v9 row_newbcast:8 row_mask:0xf bank_mask:0xf bound_ctrl:1
	v_fmac_f32_dpp v18, v33, v8 row_newbcast:9 row_mask:0xf bank_mask:0xf bound_ctrl:1
	v_fmac_f32_dpp v23, v33, v7 row_newbcast:10 row_mask:0xf bank_mask:0xf bound_ctrl:1
	v_fmac_f32_dpp v32, v33, v6 row_newbcast:11 row_mask:0xf bank_mask:0xf bound_ctrl:1
	s_nop 0
	v_fmac_f32_dpp v22, v33, v5 row_newbcast:12 row_mask:0xf bank_mask:0xf bound_ctrl:1
	v_fmac_f32_dpp v18, v33, v4 row_newbcast:13 row_mask:0xf bank_mask:0xf bound_ctrl:1
	v_fmac_f32_dpp v23, v33, v3 row_newbcast:14 row_mask:0xf bank_mask:0xf bound_ctrl:1
	v_fmac_f32_dpp v32, v33, v2 row_newbcast:15 row_mask:0xf bank_mask:0xf bound_ctrl:1
	s_waitcnt lgkmcnt(0)
	v_mov_b32_e32 v39, v224
	ds_read_b32 v33, v19 offset:23296
	ds_read2st64_b32 v[28:29], v21 offset0:27 offset1:43
	ds_read2st64_b32 v[30:31], v21 offset0:59 offset1:75
	v_mul_f32_dpp v34, v24, v17 row_newbcast:0 row_mask:0xf bank_mask:0xf bound_ctrl:1
	v_mul_f32_dpp v35, v24, v16 row_newbcast:1 row_mask:0xf bank_mask:0xf bound_ctrl:1
	v_mul_f32_dpp v40, v24, v15 row_newbcast:2 row_mask:0xf bank_mask:0xf bound_ctrl:1
	v_mul_f32_dpp v41, v24, v14 row_newbcast:3 row_mask:0xf bank_mask:0xf bound_ctrl:1
	v_fmac_f32_e32 v39, s67, v37
	v_fmac_f32_dpp v34, v24, v13 row_newbcast:4 row_mask:0xf bank_mask:0xf bound_ctrl:1
	v_fmac_f32_dpp v35, v24, v12 row_newbcast:5 row_mask:0xf bank_mask:0xf bound_ctrl:1
	v_fmac_f32_dpp v40, v24, v11 row_newbcast:6 row_mask:0xf bank_mask:0xf bound_ctrl:1
	v_fmac_f32_dpp v41, v24, v10 row_newbcast:7 row_mask:0xf bank_mask:0xf bound_ctrl:1
	v_fmac_f32_e32 v39, s66, v36
	v_fmac_f32_dpp v34, v24, v9 row_newbcast:8 row_mask:0xf bank_mask:0xf bound_ctrl:1
	v_fmac_f32_dpp v35, v24, v8 row_newbcast:9 row_mask:0xf bank_mask:0xf bound_ctrl:1
	v_fmac_f32_dpp v40, v24, v7 row_newbcast:10 row_mask:0xf bank_mask:0xf bound_ctrl:1
	v_fmac_f32_dpp v41, v24, v6 row_newbcast:11 row_mask:0xf bank_mask:0xf bound_ctrl:1
	s_nop 0
	v_fmac_f32_dpp v34, v24, v5 row_newbcast:12 row_mask:0xf bank_mask:0xf bound_ctrl:1
	v_fmac_f32_dpp v35, v24, v4 row_newbcast:13 row_mask:0xf bank_mask:0xf bound_ctrl:1
	v_fmac_f32_dpp v40, v24, v3 row_newbcast:14 row_mask:0xf bank_mask:0xf bound_ctrl:1
	v_fmac_f32_dpp v41, v24, v2 row_newbcast:15 row_mask:0xf bank_mask:0xf bound_ctrl:1
	v_fmac_f32_dpp v17, v25, v39 row_newbcast:0 row_mask:0xf bank_mask:0xf bound_ctrl:1
	v_fmac_f32_dpp v16, v25, v39 row_newbcast:1 row_mask:0xf bank_mask:0xf bound_ctrl:1
	v_fmac_f32_dpp v15, v25, v39 row_newbcast:2 row_mask:0xf bank_mask:0xf bound_ctrl:1
	v_fmac_f32_dpp v14, v25, v39 row_newbcast:3 row_mask:0xf bank_mask:0xf bound_ctrl:1
	v_fmac_f32_dpp v13, v25, v39 row_newbcast:4 row_mask:0xf bank_mask:0xf bound_ctrl:1
	v_fmac_f32_dpp v12, v25, v39 row_newbcast:5 row_mask:0xf bank_mask:0xf bound_ctrl:1
	v_fmac_f32_dpp v11, v25, v39 row_newbcast:6 row_mask:0xf bank_mask:0xf bound_ctrl:1
	v_fmac_f32_dpp v10, v25, v39 row_newbcast:7 row_mask:0xf bank_mask:0xf bound_ctrl:1
	v_fmac_f32_dpp v9, v25, v39 row_newbcast:8 row_mask:0xf bank_mask:0xf bound_ctrl:1
	v_fmac_f32_dpp v8, v25, v39 row_newbcast:9 row_mask:0xf bank_mask:0xf bound_ctrl:1
	v_fmac_f32_dpp v7, v25, v39 row_newbcast:10 row_mask:0xf bank_mask:0xf bound_ctrl:1
	v_fmac_f32_dpp v6, v25, v39 row_newbcast:11 row_mask:0xf bank_mask:0xf bound_ctrl:1
	v_fmac_f32_dpp v5, v25, v39 row_newbcast:12 row_mask:0xf bank_mask:0xf bound_ctrl:1
	v_fmac_f32_dpp v4, v25, v39 row_newbcast:13 row_mask:0xf bank_mask:0xf bound_ctrl:1
	v_fmac_f32_dpp v3, v25, v39 row_newbcast:14 row_mask:0xf bank_mask:0xf bound_ctrl:1
	v_fmac_f32_dpp v2, v25, v39 row_newbcast:15 row_mask:0xf bank_mask:0xf bound_ctrl:1
	s_nop 0
	v_add_f32 v34, v34, v35
	v_add_f32 v40, v40, v41
	s_nop 0
	v_add_f32 v34, v34, v40
	v_add_f32 v22, v22, v18
	v_add_f32 v23, v23, v32
	v_mfma_f32_16x16x4_f32 v[224:227], v228, v34, 0
	ds_write_b64 v20, v[22:23] offset:18432
	v_fmac_f32_dpp v17, v26, v38 row_newbcast:0 row_mask:0xf bank_mask:0xf bound_ctrl:1
	v_fmac_f32_dpp v16, v26, v38 row_newbcast:1 row_mask:0xf bank_mask:0xf bound_ctrl:1
	v_fmac_f32_dpp v15, v26, v38 row_newbcast:2 row_mask:0xf bank_mask:0xf bound_ctrl:1
	v_fmac_f32_dpp v14, v26, v38 row_newbcast:3 row_mask:0xf bank_mask:0xf bound_ctrl:1
	v_fmac_f32_dpp v13, v26, v38 row_newbcast:4 row_mask:0xf bank_mask:0xf bound_ctrl:1
	v_fmac_f32_dpp v12, v26, v38 row_newbcast:5 row_mask:0xf bank_mask:0xf bound_ctrl:1
	v_fmac_f32_dpp v11, v26, v38 row_newbcast:6 row_mask:0xf bank_mask:0xf bound_ctrl:1
	v_fmac_f32_dpp v10, v26, v38 row_newbcast:7 row_mask:0xf bank_mask:0xf bound_ctrl:1
	v_fmac_f32_dpp v9, v26, v38 row_newbcast:8 row_mask:0xf bank_mask:0xf bound_ctrl:1
	v_fmac_f32_dpp v8, v26, v38 row_newbcast:9 row_mask:0xf bank_mask:0xf bound_ctrl:1
	v_fmac_f32_dpp v7, v26, v38 row_newbcast:10 row_mask:0xf bank_mask:0xf bound_ctrl:1
	v_fmac_f32_dpp v6, v26, v38 row_newbcast:11 row_mask:0xf bank_mask:0xf bound_ctrl:1
	v_fmac_f32_dpp v5, v26, v38 row_newbcast:12 row_mask:0xf bank_mask:0xf bound_ctrl:1
	v_fmac_f32_dpp v4, v26, v38 row_newbcast:13 row_mask:0xf bank_mask:0xf bound_ctrl:1
	v_fmac_f32_dpp v3, v26, v38 row_newbcast:14 row_mask:0xf bank_mask:0xf bound_ctrl:1
	v_fmac_f32_dpp v2, v26, v38 row_newbcast:15 row_mask:0xf bank_mask:0xf bound_ctrl:1
	v_mul_f32_dpp v22, v27, v17 row_newbcast:0 row_mask:0xf bank_mask:0xf bound_ctrl:1
	v_mul_f32_dpp v18, v27, v16 row_newbcast:1 row_mask:0xf bank_mask:0xf bound_ctrl:1
	v_mul_f32_dpp v23, v27, v15 row_newbcast:2 row_mask:0xf bank_mask:0xf bound_ctrl:1
	v_mul_f32_dpp v32, v27, v14 row_newbcast:3 row_mask:0xf bank_mask:0xf bound_ctrl:1
	v_fmac_f32_dpp v22, v27, v13 row_newbcast:4 row_mask:0xf bank_mask:0xf bound_ctrl:1
	v_fmac_f32_dpp v18, v27, v12 row_newbcast:5 row_mask:0xf bank_mask:0xf bound_ctrl:1
	v_fmac_f32_dpp v23, v27, v11 row_newbcast:6 row_mask:0xf bank_mask:0xf bound_ctrl:1
	v_fmac_f32_dpp v32, v27, v10 row_newbcast:7 row_mask:0xf bank_mask:0xf bound_ctrl:1
	s_nop 0
	v_fmac_f32_dpp v22, v27, v9 row_newbcast:8 row_mask:0xf bank_mask:0xf bound_ctrl:1
	v_fmac_f32_dpp v18, v27, v8 row_newbcast:9 row_mask:0xf bank_mask:0xf bound_ctrl:1
	v_fmac_f32_dpp v23, v27, v7 row_newbcast:10 row_mask:0xf bank_mask:0xf bound_ctrl:1
	v_fmac_f32_dpp v32, v27, v6 row_newbcast:11 row_mask:0xf bank_mask:0xf bound_ctrl:1
	s_nop 0
	v_fmac_f32_dpp v22, v27, v5 row_newbcast:12 row_mask:0xf bank_mask:0xf bound_ctrl:1
	v_fmac_f32_dpp v18, v27, v4 row_newbcast:13 row_mask:0xf bank_mask:0xf bound_ctrl:1
	v_fmac_f32_dpp v23, v27, v3 row_newbcast:14 row_mask:0xf bank_mask:0xf bound_ctrl:1
	v_fmac_f32_dpp v32, v27, v2 row_newbcast:15 row_mask:0xf bank_mask:0xf bound_ctrl:1
	s_waitcnt lgkmcnt(0)
	v_mov_b32_e32 v34, v224
	ds_read_b32 v35, v19 offset:23552
	ds_read2st64_b32 v[24:25], v21 offset0:28 offset1:44
	ds_read2st64_b32 v[26:27], v21 offset0:60 offset1:76
	v_mul_f32_dpp v36, v28, v17 row_newbcast:0 row_mask:0xf bank_mask:0xf bound_ctrl:1
	v_mul_f32_dpp v37, v28, v16 row_newbcast:1 row_mask:0xf bank_mask:0xf bound_ctrl:1
	v_mul_f32_dpp v40, v28, v15 row_newbcast:2 row_mask:0xf bank_mask:0xf bound_ctrl:1
	v_mul_f32_dpp v41, v28, v14 row_newbcast:3 row_mask:0xf bank_mask:0xf bound_ctrl:1
	v_fmac_f32_e32 v34, s65, v39
	v_fmac_f32_dpp v36, v28, v13 row_newbcast:4 row_mask:0xf bank_mask:0xf bound_ctrl:1
	v_fmac_f32_dpp v37, v28, v12 row_newbcast:5 row_mask:0xf bank_mask:0xf bound_ctrl:1
	v_fmac_f32_dpp v40, v28, v11 row_newbcast:6 row_mask:0xf bank_mask:0xf bound_ctrl:1
	v_fmac_f32_dpp v41, v28, v10 row_newbcast:7 row_mask:0xf bank_mask:0xf bound_ctrl:1
	v_fmac_f32_e32 v34, s64, v38
	v_fmac_f32_dpp v36, v28, v9 row_newbcast:8 row_mask:0xf bank_mask:0xf bound_ctrl:1
	v_fmac_f32_dpp v37, v28, v8 row_newbcast:9 row_mask:0xf bank_mask:0xf bound_ctrl:1
	v_fmac_f32_dpp v40, v28, v7 row_newbcast:10 row_mask:0xf bank_mask:0xf bound_ctrl:1
	v_fmac_f32_dpp v41, v28, v6 row_newbcast:11 row_mask:0xf bank_mask:0xf bound_ctrl:1
	s_nop 0
	v_fmac_f32_dpp v36, v28, v5 row_newbcast:12 row_mask:0xf bank_mask:0xf bound_ctrl:1
	v_fmac_f32_dpp v37, v28, v4 row_newbcast:13 row_mask:0xf bank_mask:0xf bound_ctrl:1
	v_fmac_f32_dpp v40, v28, v3 row_newbcast:14 row_mask:0xf bank_mask:0xf bound_ctrl:1
	v_fmac_f32_dpp v41, v28, v2 row_newbcast:15 row_mask:0xf bank_mask:0xf bound_ctrl:1
	v_fmac_f32_dpp v17, v29, v34 row_newbcast:0 row_mask:0xf bank_mask:0xf bound_ctrl:1
	v_fmac_f32_dpp v16, v29, v34 row_newbcast:1 row_mask:0xf bank_mask:0xf bound_ctrl:1
	v_fmac_f32_dpp v15, v29, v34 row_newbcast:2 row_mask:0xf bank_mask:0xf bound_ctrl:1
	v_fmac_f32_dpp v14, v29, v34 row_newbcast:3 row_mask:0xf bank_mask:0xf bound_ctrl:1
	v_fmac_f32_dpp v13, v29, v34 row_newbcast:4 row_mask:0xf bank_mask:0xf bound_ctrl:1
	v_fmac_f32_dpp v12, v29, v34 row_newbcast:5 row_mask:0xf bank_mask:0xf bound_ctrl:1
	v_fmac_f32_dpp v11, v29, v34 row_newbcast:6 row_mask:0xf bank_mask:0xf bound_ctrl:1
	v_fmac_f32_dpp v10, v29, v34 row_newbcast:7 row_mask:0xf bank_mask:0xf bound_ctrl:1
	v_fmac_f32_dpp v9, v29, v34 row_newbcast:8 row_mask:0xf bank_mask:0xf bound_ctrl:1
	v_fmac_f32_dpp v8, v29, v34 row_newbcast:9 row_mask:0xf bank_mask:0xf bound_ctrl:1
	v_fmac_f32_dpp v7, v29, v34 row_newbcast:10 row_mask:0xf bank_mask:0xf bound_ctrl:1
	v_fmac_f32_dpp v6, v29, v34 row_newbcast:11 row_mask:0xf bank_mask:0xf bound_ctrl:1
	v_fmac_f32_dpp v5, v29, v34 row_newbcast:12 row_mask:0xf bank_mask:0xf bound_ctrl:1
	v_fmac_f32_dpp v4, v29, v34 row_newbcast:13 row_mask:0xf bank_mask:0xf bound_ctrl:1
	v_fmac_f32_dpp v3, v29, v34 row_newbcast:14 row_mask:0xf bank_mask:0xf bound_ctrl:1
	v_fmac_f32_dpp v2, v29, v34 row_newbcast:15 row_mask:0xf bank_mask:0xf bound_ctrl:1
	s_nop 0
	v_add_f32 v36, v36, v37
	v_add_f32 v40, v40, v41
	s_nop 0
	v_add_f32 v36, v36, v40
	v_add_f32 v22, v22, v18
	v_add_f32 v23, v23, v32
	v_mfma_f32_16x16x4_f32 v[224:227], v228, v36, 0
	ds_write_b64 v20, v[22:23] offset:20480
	v_fmac_f32_dpp v17, v30, v33 row_newbcast:0 row_mask:0xf bank_mask:0xf bound_ctrl:1
	v_fmac_f32_dpp v16, v30, v33 row_newbcast:1 row_mask:0xf bank_mask:0xf bound_ctrl:1
	v_fmac_f32_dpp v15, v30, v33 row_newbcast:2 row_mask:0xf bank_mask:0xf bound_ctrl:1
	v_fmac_f32_dpp v14, v30, v33 row_newbcast:3 row_mask:0xf bank_mask:0xf bound_ctrl:1
	v_fmac_f32_dpp v13, v30, v33 row_newbcast:4 row_mask:0xf bank_mask:0xf bound_ctrl:1
	v_fmac_f32_dpp v12, v30, v33 row_newbcast:5 row_mask:0xf bank_mask:0xf bound_ctrl:1
	v_fmac_f32_dpp v11, v30, v33 row_newbcast:6 row_mask:0xf bank_mask:0xf bound_ctrl:1
	v_fmac_f32_dpp v10, v30, v33 row_newbcast:7 row_mask:0xf bank_mask:0xf bound_ctrl:1
	v_fmac_f32_dpp v9, v30, v33 row_newbcast:8 row_mask:0xf bank_mask:0xf bound_ctrl:1
	v_fmac_f32_dpp v8, v30, v33 row_newbcast:9 row_mask:0xf bank_mask:0xf bound_ctrl:1
	v_fmac_f32_dpp v7, v30, v33 row_newbcast:10 row_mask:0xf bank_mask:0xf bound_ctrl:1
	v_fmac_f32_dpp v6, v30, v33 row_newbcast:11 row_mask:0xf bank_mask:0xf bound_ctrl:1
	v_fmac_f32_dpp v5, v30, v33 row_newbcast:12 row_mask:0xf bank_mask:0xf bound_ctrl:1
	v_fmac_f32_dpp v4, v30, v33 row_newbcast:13 row_mask:0xf bank_mask:0xf bound_ctrl:1
	v_fmac_f32_dpp v3, v30, v33 row_newbcast:14 row_mask:0xf bank_mask:0xf bound_ctrl:1
	v_fmac_f32_dpp v2, v30, v33 row_newbcast:15 row_mask:0xf bank_mask:0xf bound_ctrl:1
	v_mul_f32_dpp v22, v31, v17 row_newbcast:0 row_mask:0xf bank_mask:0xf bound_ctrl:1
	v_mul_f32_dpp v18, v31, v16 row_newbcast:1 row_mask:0xf bank_mask:0xf bound_ctrl:1
	v_mul_f32_dpp v23, v31, v15 row_newbcast:2 row_mask:0xf bank_mask:0xf bound_ctrl:1
	v_mul_f32_dpp v32, v31, v14 row_newbcast:3 row_mask:0xf bank_mask:0xf bound_ctrl:1
	v_fmac_f32_dpp v22, v31, v13 row_newbcast:4 row_mask:0xf bank_mask:0xf bound_ctrl:1
	v_fmac_f32_dpp v18, v31, v12 row_newbcast:5 row_mask:0xf bank_mask:0xf bound_ctrl:1
	v_fmac_f32_dpp v23, v31, v11 row_newbcast:6 row_mask:0xf bank_mask:0xf bound_ctrl:1
	v_fmac_f32_dpp v32, v31, v10 row_newbcast:7 row_mask:0xf bank_mask:0xf bound_ctrl:1
	s_nop 0
	v_fmac_f32_dpp v22, v31, v9 row_newbcast:8 row_mask:0xf bank_mask:0xf bound_ctrl:1
	v_fmac_f32_dpp v18, v31, v8 row_newbcast:9 row_mask:0xf bank_mask:0xf bound_ctrl:1
	v_fmac_f32_dpp v23, v31, v7 row_newbcast:10 row_mask:0xf bank_mask:0xf bound_ctrl:1
	v_fmac_f32_dpp v32, v31, v6 row_newbcast:11 row_mask:0xf bank_mask:0xf bound_ctrl:1
	s_nop 0
	v_fmac_f32_dpp v22, v31, v5 row_newbcast:12 row_mask:0xf bank_mask:0xf bound_ctrl:1
	v_fmac_f32_dpp v18, v31, v4 row_newbcast:13 row_mask:0xf bank_mask:0xf bound_ctrl:1
	v_fmac_f32_dpp v23, v31, v3 row_newbcast:14 row_mask:0xf bank_mask:0xf bound_ctrl:1
	v_fmac_f32_dpp v32, v31, v2 row_newbcast:15 row_mask:0xf bank_mask:0xf bound_ctrl:1
	s_waitcnt lgkmcnt(0)
	v_mov_b32_e32 v36, v224
	ds_read_b32 v37, v19 offset:23808
	ds_read2st64_b32 v[28:29], v21 offset0:29 offset1:45
	ds_read2st64_b32 v[30:31], v21 offset0:61 offset1:77
	v_mul_f32_dpp v38, v24, v17 row_newbcast:0 row_mask:0xf bank_mask:0xf bound_ctrl:1
	v_mul_f32_dpp v39, v24, v16 row_newbcast:1 row_mask:0xf bank_mask:0xf bound_ctrl:1
	v_mul_f32_dpp v40, v24, v15 row_newbcast:2 row_mask:0xf bank_mask:0xf bound_ctrl:1
	v_mul_f32_dpp v41, v24, v14 row_newbcast:3 row_mask:0xf bank_mask:0xf bound_ctrl:1
	v_fmac_f32_e32 v36, s63, v34
	v_fmac_f32_dpp v38, v24, v13 row_newbcast:4 row_mask:0xf bank_mask:0xf bound_ctrl:1
	v_fmac_f32_dpp v39, v24, v12 row_newbcast:5 row_mask:0xf bank_mask:0xf bound_ctrl:1
	v_fmac_f32_dpp v40, v24, v11 row_newbcast:6 row_mask:0xf bank_mask:0xf bound_ctrl:1
	v_fmac_f32_dpp v41, v24, v10 row_newbcast:7 row_mask:0xf bank_mask:0xf bound_ctrl:1
	v_fmac_f32_e32 v36, s62, v33
	v_fmac_f32_dpp v38, v24, v9 row_newbcast:8 row_mask:0xf bank_mask:0xf bound_ctrl:1
	v_fmac_f32_dpp v39, v24, v8 row_newbcast:9 row_mask:0xf bank_mask:0xf bound_ctrl:1
	v_fmac_f32_dpp v40, v24, v7 row_newbcast:10 row_mask:0xf bank_mask:0xf bound_ctrl:1
	v_fmac_f32_dpp v41, v24, v6 row_newbcast:11 row_mask:0xf bank_mask:0xf bound_ctrl:1
	s_nop 0
	v_fmac_f32_dpp v38, v24, v5 row_newbcast:12 row_mask:0xf bank_mask:0xf bound_ctrl:1
	v_fmac_f32_dpp v39, v24, v4 row_newbcast:13 row_mask:0xf bank_mask:0xf bound_ctrl:1
	v_fmac_f32_dpp v40, v24, v3 row_newbcast:14 row_mask:0xf bank_mask:0xf bound_ctrl:1
	v_fmac_f32_dpp v41, v24, v2 row_newbcast:15 row_mask:0xf bank_mask:0xf bound_ctrl:1
	v_fmac_f32_dpp v17, v25, v36 row_newbcast:0 row_mask:0xf bank_mask:0xf bound_ctrl:1
	v_fmac_f32_dpp v16, v25, v36 row_newbcast:1 row_mask:0xf bank_mask:0xf bound_ctrl:1
	v_fmac_f32_dpp v15, v25, v36 row_newbcast:2 row_mask:0xf bank_mask:0xf bound_ctrl:1
	v_fmac_f32_dpp v14, v25, v36 row_newbcast:3 row_mask:0xf bank_mask:0xf bound_ctrl:1
	v_fmac_f32_dpp v13, v25, v36 row_newbcast:4 row_mask:0xf bank_mask:0xf bound_ctrl:1
	v_fmac_f32_dpp v12, v25, v36 row_newbcast:5 row_mask:0xf bank_mask:0xf bound_ctrl:1
	v_fmac_f32_dpp v11, v25, v36 row_newbcast:6 row_mask:0xf bank_mask:0xf bound_ctrl:1
	v_fmac_f32_dpp v10, v25, v36 row_newbcast:7 row_mask:0xf bank_mask:0xf bound_ctrl:1
	v_fmac_f32_dpp v9, v25, v36 row_newbcast:8 row_mask:0xf bank_mask:0xf bound_ctrl:1
	v_fmac_f32_dpp v8, v25, v36 row_newbcast:9 row_mask:0xf bank_mask:0xf bound_ctrl:1
	v_fmac_f32_dpp v7, v25, v36 row_newbcast:10 row_mask:0xf bank_mask:0xf bound_ctrl:1
	v_fmac_f32_dpp v6, v25, v36 row_newbcast:11 row_mask:0xf bank_mask:0xf bound_ctrl:1
	v_fmac_f32_dpp v5, v25, v36 row_newbcast:12 row_mask:0xf bank_mask:0xf bound_ctrl:1
	v_fmac_f32_dpp v4, v25, v36 row_newbcast:13 row_mask:0xf bank_mask:0xf bound_ctrl:1
	v_fmac_f32_dpp v3, v25, v36 row_newbcast:14 row_mask:0xf bank_mask:0xf bound_ctrl:1
	v_fmac_f32_dpp v2, v25, v36 row_newbcast:15 row_mask:0xf bank_mask:0xf bound_ctrl:1
	s_nop 0
	v_add_f32 v38, v38, v39
	v_add_f32 v40, v40, v41
	s_nop 0
	v_add_f32 v38, v38, v40
	v_add_f32 v22, v22, v18
	v_add_f32 v23, v23, v32
	v_mfma_f32_16x16x4_f32 v[224:227], v228, v38, 0
	ds_write_b64 v20, v[22:23] offset:22528
	v_fmac_f32_dpp v17, v26, v35 row_newbcast:0 row_mask:0xf bank_mask:0xf bound_ctrl:1
	v_fmac_f32_dpp v16, v26, v35 row_newbcast:1 row_mask:0xf bank_mask:0xf bound_ctrl:1
	v_fmac_f32_dpp v15, v26, v35 row_newbcast:2 row_mask:0xf bank_mask:0xf bound_ctrl:1
	v_fmac_f32_dpp v14, v26, v35 row_newbcast:3 row_mask:0xf bank_mask:0xf bound_ctrl:1
	v_fmac_f32_dpp v13, v26, v35 row_newbcast:4 row_mask:0xf bank_mask:0xf bound_ctrl:1
	v_fmac_f32_dpp v12, v26, v35 row_newbcast:5 row_mask:0xf bank_mask:0xf bound_ctrl:1
	v_fmac_f32_dpp v11, v26, v35 row_newbcast:6 row_mask:0xf bank_mask:0xf bound_ctrl:1
	v_fmac_f32_dpp v10, v26, v35 row_newbcast:7 row_mask:0xf bank_mask:0xf bound_ctrl:1
	v_fmac_f32_dpp v9, v26, v35 row_newbcast:8 row_mask:0xf bank_mask:0xf bound_ctrl:1
	v_fmac_f32_dpp v8, v26, v35 row_newbcast:9 row_mask:0xf bank_mask:0xf bound_ctrl:1
	v_fmac_f32_dpp v7, v26, v35 row_newbcast:10 row_mask:0xf bank_mask:0xf bound_ctrl:1
	v_fmac_f32_dpp v6, v26, v35 row_newbcast:11 row_mask:0xf bank_mask:0xf bound_ctrl:1
	v_fmac_f32_dpp v5, v26, v35 row_newbcast:12 row_mask:0xf bank_mask:0xf bound_ctrl:1
	v_fmac_f32_dpp v4, v26, v35 row_newbcast:13 row_mask:0xf bank_mask:0xf bound_ctrl:1
	v_fmac_f32_dpp v3, v26, v35 row_newbcast:14 row_mask:0xf bank_mask:0xf bound_ctrl:1
	v_fmac_f32_dpp v2, v26, v35 row_newbcast:15 row_mask:0xf bank_mask:0xf bound_ctrl:1
	v_mul_f32_dpp v22, v27, v17 row_newbcast:0 row_mask:0xf bank_mask:0xf bound_ctrl:1
	v_mul_f32_dpp v18, v27, v16 row_newbcast:1 row_mask:0xf bank_mask:0xf bound_ctrl:1
	v_mul_f32_dpp v23, v27, v15 row_newbcast:2 row_mask:0xf bank_mask:0xf bound_ctrl:1
	v_mul_f32_dpp v32, v27, v14 row_newbcast:3 row_mask:0xf bank_mask:0xf bound_ctrl:1
	v_fmac_f32_dpp v22, v27, v13 row_newbcast:4 row_mask:0xf bank_mask:0xf bound_ctrl:1
	v_fmac_f32_dpp v18, v27, v12 row_newbcast:5 row_mask:0xf bank_mask:0xf bound_ctrl:1
	v_fmac_f32_dpp v23, v27, v11 row_newbcast:6 row_mask:0xf bank_mask:0xf bound_ctrl:1
	v_fmac_f32_dpp v32, v27, v10 row_newbcast:7 row_mask:0xf bank_mask:0xf bound_ctrl:1
	s_nop 0
	v_fmac_f32_dpp v22, v27, v9 row_newbcast:8 row_mask:0xf bank_mask:0xf bound_ctrl:1
	v_fmac_f32_dpp v18, v27, v8 row_newbcast:9 row_mask:0xf bank_mask:0xf bound_ctrl:1
	v_fmac_f32_dpp v23, v27, v7 row_newbcast:10 row_mask:0xf bank_mask:0xf bound_ctrl:1
	v_fmac_f32_dpp v32, v27, v6 row_newbcast:11 row_mask:0xf bank_mask:0xf bound_ctrl:1
	s_nop 0
	v_fmac_f32_dpp v22, v27, v5 row_newbcast:12 row_mask:0xf bank_mask:0xf bound_ctrl:1
	v_fmac_f32_dpp v18, v27, v4 row_newbcast:13 row_mask:0xf bank_mask:0xf bound_ctrl:1
	v_fmac_f32_dpp v23, v27, v3 row_newbcast:14 row_mask:0xf bank_mask:0xf bound_ctrl:1
	v_fmac_f32_dpp v32, v27, v2 row_newbcast:15 row_mask:0xf bank_mask:0xf bound_ctrl:1
	s_waitcnt lgkmcnt(0)
	v_mov_b32_e32 v38, v224
	ds_read_b32 v34, v19 offset:24064
	ds_read2st64_b32 v[24:25], v21 offset0:30 offset1:46
	ds_read2st64_b32 v[26:27], v21 offset0:62 offset1:78
	v_mul_f32_dpp v39, v28, v17 row_newbcast:0 row_mask:0xf bank_mask:0xf bound_ctrl:1
	v_mul_f32_dpp v33, v28, v16 row_newbcast:1 row_mask:0xf bank_mask:0xf bound_ctrl:1
	v_mul_f32_dpp v40, v28, v15 row_newbcast:2 row_mask:0xf bank_mask:0xf bound_ctrl:1
	v_mul_f32_dpp v41, v28, v14 row_newbcast:3 row_mask:0xf bank_mask:0xf bound_ctrl:1
	v_fmac_f32_e32 v38, s59, v36
	v_fmac_f32_dpp v39, v28, v13 row_newbcast:4 row_mask:0xf bank_mask:0xf bound_ctrl:1
	v_fmac_f32_dpp v33, v28, v12 row_newbcast:5 row_mask:0xf bank_mask:0xf bound_ctrl:1
	v_fmac_f32_dpp v40, v28, v11 row_newbcast:6 row_mask:0xf bank_mask:0xf bound_ctrl:1
	v_fmac_f32_dpp v41, v28, v10 row_newbcast:7 row_mask:0xf bank_mask:0xf bound_ctrl:1
	v_fmac_f32_e32 v38, s58, v35
	v_fmac_f32_dpp v39, v28, v9 row_newbcast:8 row_mask:0xf bank_mask:0xf bound_ctrl:1
	v_fmac_f32_dpp v33, v28, v8 row_newbcast:9 row_mask:0xf bank_mask:0xf bound_ctrl:1
	v_fmac_f32_dpp v40, v28, v7 row_newbcast:10 row_mask:0xf bank_mask:0xf bound_ctrl:1
	v_fmac_f32_dpp v41, v28, v6 row_newbcast:11 row_mask:0xf bank_mask:0xf bound_ctrl:1
	s_nop 0
	v_fmac_f32_dpp v39, v28, v5 row_newbcast:12 row_mask:0xf bank_mask:0xf bound_ctrl:1
	v_fmac_f32_dpp v33, v28, v4 row_newbcast:13 row_mask:0xf bank_mask:0xf bound_ctrl:1
	v_fmac_f32_dpp v40, v28, v3 row_newbcast:14 row_mask:0xf bank_mask:0xf bound_ctrl:1
	v_fmac_f32_dpp v41, v28, v2 row_newbcast:15 row_mask:0xf bank_mask:0xf bound_ctrl:1
	v_fmac_f32_dpp v17, v29, v38 row_newbcast:0 row_mask:0xf bank_mask:0xf bound_ctrl:1
	v_fmac_f32_dpp v16, v29, v38 row_newbcast:1 row_mask:0xf bank_mask:0xf bound_ctrl:1
	v_fmac_f32_dpp v15, v29, v38 row_newbcast:2 row_mask:0xf bank_mask:0xf bound_ctrl:1
	v_fmac_f32_dpp v14, v29, v38 row_newbcast:3 row_mask:0xf bank_mask:0xf bound_ctrl:1
	v_fmac_f32_dpp v13, v29, v38 row_newbcast:4 row_mask:0xf bank_mask:0xf bound_ctrl:1
	v_fmac_f32_dpp v12, v29, v38 row_newbcast:5 row_mask:0xf bank_mask:0xf bound_ctrl:1
	v_fmac_f32_dpp v11, v29, v38 row_newbcast:6 row_mask:0xf bank_mask:0xf bound_ctrl:1
	v_fmac_f32_dpp v10, v29, v38 row_newbcast:7 row_mask:0xf bank_mask:0xf bound_ctrl:1
	v_fmac_f32_dpp v9, v29, v38 row_newbcast:8 row_mask:0xf bank_mask:0xf bound_ctrl:1
	v_fmac_f32_dpp v8, v29, v38 row_newbcast:9 row_mask:0xf bank_mask:0xf bound_ctrl:1
	v_fmac_f32_dpp v7, v29, v38 row_newbcast:10 row_mask:0xf bank_mask:0xf bound_ctrl:1
	v_fmac_f32_dpp v6, v29, v38 row_newbcast:11 row_mask:0xf bank_mask:0xf bound_ctrl:1
	v_fmac_f32_dpp v5, v29, v38 row_newbcast:12 row_mask:0xf bank_mask:0xf bound_ctrl:1
	v_fmac_f32_dpp v4, v29, v38 row_newbcast:13 row_mask:0xf bank_mask:0xf bound_ctrl:1
	v_fmac_f32_dpp v3, v29, v38 row_newbcast:14 row_mask:0xf bank_mask:0xf bound_ctrl:1
	v_fmac_f32_dpp v2, v29, v38 row_newbcast:15 row_mask:0xf bank_mask:0xf bound_ctrl:1
	s_nop 0
	v_add_f32 v39, v39, v33
	v_add_f32 v40, v40, v41
	s_nop 0
	v_add_f32 v39, v39, v40
	v_add_f32 v22, v22, v18
	v_add_f32 v23, v23, v32
	v_mfma_f32_16x16x4_f32 v[224:227], v228, v39, 0
	ds_write_b64 v20, v[22:23] offset:24576
	v_fmac_f32_dpp v17, v30, v37 row_newbcast:0 row_mask:0xf bank_mask:0xf bound_ctrl:1
	v_fmac_f32_dpp v16, v30, v37 row_newbcast:1 row_mask:0xf bank_mask:0xf bound_ctrl:1
	v_fmac_f32_dpp v15, v30, v37 row_newbcast:2 row_mask:0xf bank_mask:0xf bound_ctrl:1
	v_fmac_f32_dpp v14, v30, v37 row_newbcast:3 row_mask:0xf bank_mask:0xf bound_ctrl:1
	v_fmac_f32_dpp v13, v30, v37 row_newbcast:4 row_mask:0xf bank_mask:0xf bound_ctrl:1
	v_fmac_f32_dpp v12, v30, v37 row_newbcast:5 row_mask:0xf bank_mask:0xf bound_ctrl:1
	v_fmac_f32_dpp v11, v30, v37 row_newbcast:6 row_mask:0xf bank_mask:0xf bound_ctrl:1
	v_fmac_f32_dpp v10, v30, v37 row_newbcast:7 row_mask:0xf bank_mask:0xf bound_ctrl:1
	v_fmac_f32_dpp v9, v30, v37 row_newbcast:8 row_mask:0xf bank_mask:0xf bound_ctrl:1
	v_fmac_f32_dpp v8, v30, v37 row_newbcast:9 row_mask:0xf bank_mask:0xf bound_ctrl:1
	v_fmac_f32_dpp v7, v30, v37 row_newbcast:10 row_mask:0xf bank_mask:0xf bound_ctrl:1
	v_fmac_f32_dpp v6, v30, v37 row_newbcast:11 row_mask:0xf bank_mask:0xf bound_ctrl:1
	v_fmac_f32_dpp v5, v30, v37 row_newbcast:12 row_mask:0xf bank_mask:0xf bound_ctrl:1
	v_fmac_f32_dpp v4, v30, v37 row_newbcast:13 row_mask:0xf bank_mask:0xf bound_ctrl:1
	v_fmac_f32_dpp v3, v30, v37 row_newbcast:14 row_mask:0xf bank_mask:0xf bound_ctrl:1
	v_fmac_f32_dpp v2, v30, v37 row_newbcast:15 row_mask:0xf bank_mask:0xf bound_ctrl:1
	v_mul_f32_dpp v28, v31, v17 row_newbcast:0 row_mask:0xf bank_mask:0xf bound_ctrl:1
	v_mul_f32_dpp v18, v31, v16 row_newbcast:1 row_mask:0xf bank_mask:0xf bound_ctrl:1
	v_mul_f32_dpp v29, v31, v15 row_newbcast:2 row_mask:0xf bank_mask:0xf bound_ctrl:1
	v_mul_f32_dpp v23, v31, v14 row_newbcast:3 row_mask:0xf bank_mask:0xf bound_ctrl:1
	v_fmac_f32_dpp v28, v31, v13 row_newbcast:4 row_mask:0xf bank_mask:0xf bound_ctrl:1
	v_fmac_f32_dpp v18, v31, v12 row_newbcast:5 row_mask:0xf bank_mask:0xf bound_ctrl:1
	v_fmac_f32_dpp v29, v31, v11 row_newbcast:6 row_mask:0xf bank_mask:0xf bound_ctrl:1
	v_fmac_f32_dpp v23, v31, v10 row_newbcast:7 row_mask:0xf bank_mask:0xf bound_ctrl:1
	s_nop 0
	v_fmac_f32_dpp v28, v31, v9 row_newbcast:8 row_mask:0xf bank_mask:0xf bound_ctrl:1
	v_fmac_f32_dpp v18, v31, v8 row_newbcast:9 row_mask:0xf bank_mask:0xf bound_ctrl:1
	v_fmac_f32_dpp v29, v31, v7 row_newbcast:10 row_mask:0xf bank_mask:0xf bound_ctrl:1
	v_fmac_f32_dpp v23, v31, v6 row_newbcast:11 row_mask:0xf bank_mask:0xf bound_ctrl:1
	s_nop 0
	v_fmac_f32_dpp v28, v31, v5 row_newbcast:12 row_mask:0xf bank_mask:0xf bound_ctrl:1
	v_fmac_f32_dpp v18, v31, v4 row_newbcast:13 row_mask:0xf bank_mask:0xf bound_ctrl:1
	v_fmac_f32_dpp v29, v31, v3 row_newbcast:14 row_mask:0xf bank_mask:0xf bound_ctrl:1
	v_fmac_f32_dpp v23, v31, v2 row_newbcast:15 row_mask:0xf bank_mask:0xf bound_ctrl:1
	s_waitcnt lgkmcnt(0)
	v_mov_b32_e32 v39, v224
	ds_read_b32 v19, v19 offset:24320
	ds_read2st64_b32 v[30:31], v21 offset0:31 offset1:47
	ds_read2st64_b32 v[32:33], v21 offset0:63 offset1:79
	v_mul_f32_dpp v22, v24, v17 row_newbcast:0 row_mask:0xf bank_mask:0xf bound_ctrl:1
	v_mul_f32_dpp v35, v24, v16 row_newbcast:1 row_mask:0xf bank_mask:0xf bound_ctrl:1
	v_mul_f32_dpp v36, v24, v15 row_newbcast:2 row_mask:0xf bank_mask:0xf bound_ctrl:1
	v_mul_f32_dpp v40, v24, v14 row_newbcast:3 row_mask:0xf bank_mask:0xf bound_ctrl:1
	v_fmac_f32_e32 v39, s57, v38
	v_fmac_f32_dpp v22, v24, v13 row_newbcast:4 row_mask:0xf bank_mask:0xf bound_ctrl:1
	v_fmac_f32_dpp v35, v24, v12 row_newbcast:5 row_mask:0xf bank_mask:0xf bound_ctrl:1
	v_fmac_f32_dpp v36, v24, v11 row_newbcast:6 row_mask:0xf bank_mask:0xf bound_ctrl:1
	v_fmac_f32_dpp v40, v24, v10 row_newbcast:7 row_mask:0xf bank_mask:0xf bound_ctrl:1
	v_fmac_f32_e32 v39, s56, v37
	v_fmac_f32_dpp v22, v24, v9 row_newbcast:8 row_mask:0xf bank_mask:0xf bound_ctrl:1
	v_fmac_f32_dpp v35, v24, v8 row_newbcast:9 row_mask:0xf bank_mask:0xf bound_ctrl:1
	v_fmac_f32_dpp v36, v24, v7 row_newbcast:10 row_mask:0xf bank_mask:0xf bound_ctrl:1
	v_fmac_f32_dpp v40, v24, v6 row_newbcast:11 row_mask:0xf bank_mask:0xf bound_ctrl:1
	s_nop 0
	v_fmac_f32_dpp v22, v24, v5 row_newbcast:12 row_mask:0xf bank_mask:0xf bound_ctrl:1
	v_fmac_f32_dpp v35, v24, v4 row_newbcast:13 row_mask:0xf bank_mask:0xf bound_ctrl:1
	v_fmac_f32_dpp v36, v24, v3 row_newbcast:14 row_mask:0xf bank_mask:0xf bound_ctrl:1
	v_fmac_f32_dpp v40, v24, v2 row_newbcast:15 row_mask:0xf bank_mask:0xf bound_ctrl:1
	v_fmac_f32_dpp v17, v25, v39 row_newbcast:0 row_mask:0xf bank_mask:0xf bound_ctrl:1
	v_fmac_f32_dpp v16, v25, v39 row_newbcast:1 row_mask:0xf bank_mask:0xf bound_ctrl:1
	v_fmac_f32_dpp v15, v25, v39 row_newbcast:2 row_mask:0xf bank_mask:0xf bound_ctrl:1
	v_fmac_f32_dpp v14, v25, v39 row_newbcast:3 row_mask:0xf bank_mask:0xf bound_ctrl:1
	v_fmac_f32_dpp v13, v25, v39 row_newbcast:4 row_mask:0xf bank_mask:0xf bound_ctrl:1
	v_fmac_f32_dpp v12, v25, v39 row_newbcast:5 row_mask:0xf bank_mask:0xf bound_ctrl:1
	v_fmac_f32_dpp v11, v25, v39 row_newbcast:6 row_mask:0xf bank_mask:0xf bound_ctrl:1
	v_fmac_f32_dpp v10, v25, v39 row_newbcast:7 row_mask:0xf bank_mask:0xf bound_ctrl:1
	v_fmac_f32_dpp v9, v25, v39 row_newbcast:8 row_mask:0xf bank_mask:0xf bound_ctrl:1
	v_fmac_f32_dpp v8, v25, v39 row_newbcast:9 row_mask:0xf bank_mask:0xf bound_ctrl:1
	v_fmac_f32_dpp v7, v25, v39 row_newbcast:10 row_mask:0xf bank_mask:0xf bound_ctrl:1
	v_fmac_f32_dpp v6, v25, v39 row_newbcast:11 row_mask:0xf bank_mask:0xf bound_ctrl:1
	v_fmac_f32_dpp v5, v25, v39 row_newbcast:12 row_mask:0xf bank_mask:0xf bound_ctrl:1
	v_fmac_f32_dpp v4, v25, v39 row_newbcast:13 row_mask:0xf bank_mask:0xf bound_ctrl:1
	v_fmac_f32_dpp v3, v25, v39 row_newbcast:14 row_mask:0xf bank_mask:0xf bound_ctrl:1
	v_fmac_f32_dpp v2, v25, v39 row_newbcast:15 row_mask:0xf bank_mask:0xf bound_ctrl:1
	s_nop 0
	v_add_f32 v22, v22, v35
	v_add_f32 v36, v36, v40
	s_nop 0
	v_add_f32 v22, v22, v36
	v_add_f32 v28, v28, v18
	v_add_f32 v29, v29, v23
	v_mfma_f32_16x16x4_f32 v[224:227], v228, v22, 0
	ds_write_b64 v20, v[28:29] offset:26624
	v_fmac_f32_dpp v17, v26, v34 row_newbcast:0 row_mask:0xf bank_mask:0xf bound_ctrl:1
	v_fmac_f32_dpp v16, v26, v34 row_newbcast:1 row_mask:0xf bank_mask:0xf bound_ctrl:1
	v_fmac_f32_dpp v15, v26, v34 row_newbcast:2 row_mask:0xf bank_mask:0xf bound_ctrl:1
	v_fmac_f32_dpp v14, v26, v34 row_newbcast:3 row_mask:0xf bank_mask:0xf bound_ctrl:1
	v_fmac_f32_dpp v13, v26, v34 row_newbcast:4 row_mask:0xf bank_mask:0xf bound_ctrl:1
	v_fmac_f32_dpp v12, v26, v34 row_newbcast:5 row_mask:0xf bank_mask:0xf bound_ctrl:1
	v_fmac_f32_dpp v11, v26, v34 row_newbcast:6 row_mask:0xf bank_mask:0xf bound_ctrl:1
	v_fmac_f32_dpp v10, v26, v34 row_newbcast:7 row_mask:0xf bank_mask:0xf bound_ctrl:1
	v_fmac_f32_dpp v9, v26, v34 row_newbcast:8 row_mask:0xf bank_mask:0xf bound_ctrl:1
	v_fmac_f32_dpp v8, v26, v34 row_newbcast:9 row_mask:0xf bank_mask:0xf bound_ctrl:1
	v_fmac_f32_dpp v7, v26, v34 row_newbcast:10 row_mask:0xf bank_mask:0xf bound_ctrl:1
	v_fmac_f32_dpp v6, v26, v34 row_newbcast:11 row_mask:0xf bank_mask:0xf bound_ctrl:1
	v_fmac_f32_dpp v5, v26, v34 row_newbcast:12 row_mask:0xf bank_mask:0xf bound_ctrl:1
	v_fmac_f32_dpp v4, v26, v34 row_newbcast:13 row_mask:0xf bank_mask:0xf bound_ctrl:1
	v_fmac_f32_dpp v3, v26, v34 row_newbcast:14 row_mask:0xf bank_mask:0xf bound_ctrl:1
	v_fmac_f32_dpp v2, v26, v34 row_newbcast:15 row_mask:0xf bank_mask:0xf bound_ctrl:1
	v_mul_f32_dpp v24, v27, v17 row_newbcast:0 row_mask:0xf bank_mask:0xf bound_ctrl:1
	v_mul_f32_dpp v23, v27, v16 row_newbcast:1 row_mask:0xf bank_mask:0xf bound_ctrl:1
	v_mul_f32_dpp v25, v27, v15 row_newbcast:2 row_mask:0xf bank_mask:0xf bound_ctrl:1
	v_mul_f32_dpp v26, v27, v14 row_newbcast:3 row_mask:0xf bank_mask:0xf bound_ctrl:1
	v_fmac_f32_dpp v24, v27, v13 row_newbcast:4 row_mask:0xf bank_mask:0xf bound_ctrl:1
	v_fmac_f32_dpp v23, v27, v12 row_newbcast:5 row_mask:0xf bank_mask:0xf bound_ctrl:1
	v_fmac_f32_dpp v25, v27, v11 row_newbcast:6 row_mask:0xf bank_mask:0xf bound_ctrl:1
	v_fmac_f32_dpp v26, v27, v10 row_newbcast:7 row_mask:0xf bank_mask:0xf bound_ctrl:1
	s_nop 0
	v_fmac_f32_dpp v24, v27, v9 row_newbcast:8 row_mask:0xf bank_mask:0xf bound_ctrl:1
	v_fmac_f32_dpp v23, v27, v8 row_newbcast:9 row_mask:0xf bank_mask:0xf bound_ctrl:1
	v_fmac_f32_dpp v25, v27, v7 row_newbcast:10 row_mask:0xf bank_mask:0xf bound_ctrl:1
	v_fmac_f32_dpp v26, v27, v6 row_newbcast:11 row_mask:0xf bank_mask:0xf bound_ctrl:1
	s_nop 0
	v_fmac_f32_dpp v24, v27, v5 row_newbcast:12 row_mask:0xf bank_mask:0xf bound_ctrl:1
	v_fmac_f32_dpp v23, v27, v4 row_newbcast:13 row_mask:0xf bank_mask:0xf bound_ctrl:1
	v_fmac_f32_dpp v25, v27, v3 row_newbcast:14 row_mask:0xf bank_mask:0xf bound_ctrl:1
	v_fmac_f32_dpp v26, v27, v2 row_newbcast:15 row_mask:0xf bank_mask:0xf bound_ctrl:1
	s_waitcnt lgkmcnt(0)
	v_mov_b32_e32 v22, v224
	v_mul_f32_dpp v18, v30, v17 row_newbcast:0 row_mask:0xf bank_mask:0xf bound_ctrl:1
	v_mul_f32_dpp v27, v30, v16 row_newbcast:1 row_mask:0xf bank_mask:0xf bound_ctrl:1
	v_mul_f32_dpp v28, v30, v15 row_newbcast:2 row_mask:0xf bank_mask:0xf bound_ctrl:1
	v_mul_f32_dpp v29, v30, v14 row_newbcast:3 row_mask:0xf bank_mask:0xf bound_ctrl:1
	s_nop 0
	v_fmac_f32_dpp v18, v30, v13 row_newbcast:4 row_mask:0xf bank_mask:0xf bound_ctrl:1
	v_fmac_f32_dpp v27, v30, v12 row_newbcast:5 row_mask:0xf bank_mask:0xf bound_ctrl:1
	v_fmac_f32_dpp v28, v30, v11 row_newbcast:6 row_mask:0xf bank_mask:0xf bound_ctrl:1
	v_fmac_f32_dpp v29, v30, v10 row_newbcast:7 row_mask:0xf bank_mask:0xf bound_ctrl:1
	v_fmac_f32_e32 v22, s53, v39
	v_fmac_f32_dpp v18, v30, v9 row_newbcast:8 row_mask:0xf bank_mask:0xf bound_ctrl:1
	v_fmac_f32_dpp v27, v30, v8 row_newbcast:9 row_mask:0xf bank_mask:0xf bound_ctrl:1
	v_fmac_f32_dpp v28, v30, v7 row_newbcast:10 row_mask:0xf bank_mask:0xf bound_ctrl:1
	v_fmac_f32_dpp v29, v30, v6 row_newbcast:11 row_mask:0xf bank_mask:0xf bound_ctrl:1
	v_fmac_f32_e32 v22, s48, v34
	v_fmac_f32_dpp v18, v30, v5 row_newbcast:12 row_mask:0xf bank_mask:0xf bound_ctrl:1
	v_fmac_f32_dpp v27, v30, v4 row_newbcast:13 row_mask:0xf bank_mask:0xf bound_ctrl:1
	v_fmac_f32_dpp v28, v30, v3 row_newbcast:14 row_mask:0xf bank_mask:0xf bound_ctrl:1
	v_fmac_f32_dpp v29, v30, v2 row_newbcast:15 row_mask:0xf bank_mask:0xf bound_ctrl:1
	v_fmac_f32_dpp v17, v31, v22 row_newbcast:0 row_mask:0xf bank_mask:0xf bound_ctrl:1
	v_fmac_f32_dpp v16, v31, v22 row_newbcast:1 row_mask:0xf bank_mask:0xf bound_ctrl:1
	v_fmac_f32_dpp v15, v31, v22 row_newbcast:2 row_mask:0xf bank_mask:0xf bound_ctrl:1
	v_fmac_f32_dpp v14, v31, v22 row_newbcast:3 row_mask:0xf bank_mask:0xf bound_ctrl:1
	v_fmac_f32_dpp v13, v31, v22 row_newbcast:4 row_mask:0xf bank_mask:0xf bound_ctrl:1
	v_fmac_f32_dpp v12, v31, v22 row_newbcast:5 row_mask:0xf bank_mask:0xf bound_ctrl:1
	v_fmac_f32_dpp v11, v31, v22 row_newbcast:6 row_mask:0xf bank_mask:0xf bound_ctrl:1
	v_fmac_f32_dpp v10, v31, v22 row_newbcast:7 row_mask:0xf bank_mask:0xf bound_ctrl:1
	v_fmac_f32_dpp v9, v31, v22 row_newbcast:8 row_mask:0xf bank_mask:0xf bound_ctrl:1
	v_fmac_f32_dpp v8, v31, v22 row_newbcast:9 row_mask:0xf bank_mask:0xf bound_ctrl:1
	v_fmac_f32_dpp v7, v31, v22 row_newbcast:10 row_mask:0xf bank_mask:0xf bound_ctrl:1
	v_fmac_f32_dpp v6, v31, v22 row_newbcast:11 row_mask:0xf bank_mask:0xf bound_ctrl:1
	v_fmac_f32_dpp v5, v31, v22 row_newbcast:12 row_mask:0xf bank_mask:0xf bound_ctrl:1
	v_fmac_f32_dpp v4, v31, v22 row_newbcast:13 row_mask:0xf bank_mask:0xf bound_ctrl:1
	v_fmac_f32_dpp v3, v31, v22 row_newbcast:14 row_mask:0xf bank_mask:0xf bound_ctrl:1
	v_fmac_f32_dpp v2, v31, v22 row_newbcast:15 row_mask:0xf bank_mask:0xf bound_ctrl:1
	s_nop 0
	v_add_f32 v18, v18, v27
	v_add_f32 v28, v28, v29
	s_nop 0
	v_add_f32 v18, v18, v28
	v_add_f32 v24, v24, v23
	v_add_f32 v25, v25, v26
	v_mfma_f32_16x16x4_f32 v[224:227], v228, v18, 0
	ds_write_b64 v20, v[24:25] offset:28672
	v_fmac_f32_dpp v17, v32, v19 row_newbcast:0 row_mask:0xf bank_mask:0xf bound_ctrl:1
	v_fmac_f32_dpp v16, v32, v19 row_newbcast:1 row_mask:0xf bank_mask:0xf bound_ctrl:1
	v_fmac_f32_dpp v15, v32, v19 row_newbcast:2 row_mask:0xf bank_mask:0xf bound_ctrl:1
	v_fmac_f32_dpp v14, v32, v19 row_newbcast:3 row_mask:0xf bank_mask:0xf bound_ctrl:1
	v_fmac_f32_dpp v13, v32, v19 row_newbcast:4 row_mask:0xf bank_mask:0xf bound_ctrl:1
	v_fmac_f32_dpp v12, v32, v19 row_newbcast:5 row_mask:0xf bank_mask:0xf bound_ctrl:1
	v_fmac_f32_dpp v11, v32, v19 row_newbcast:6 row_mask:0xf bank_mask:0xf bound_ctrl:1
	v_fmac_f32_dpp v10, v32, v19 row_newbcast:7 row_mask:0xf bank_mask:0xf bound_ctrl:1
	v_fmac_f32_dpp v9, v32, v19 row_newbcast:8 row_mask:0xf bank_mask:0xf bound_ctrl:1
	v_fmac_f32_dpp v8, v32, v19 row_newbcast:9 row_mask:0xf bank_mask:0xf bound_ctrl:1
	v_fmac_f32_dpp v7, v32, v19 row_newbcast:10 row_mask:0xf bank_mask:0xf bound_ctrl:1
	v_fmac_f32_dpp v6, v32, v19 row_newbcast:11 row_mask:0xf bank_mask:0xf bound_ctrl:1
	v_fmac_f32_dpp v5, v32, v19 row_newbcast:12 row_mask:0xf bank_mask:0xf bound_ctrl:1
	v_fmac_f32_dpp v4, v32, v19 row_newbcast:13 row_mask:0xf bank_mask:0xf bound_ctrl:1
	v_fmac_f32_dpp v3, v32, v19 row_newbcast:14 row_mask:0xf bank_mask:0xf bound_ctrl:1
	v_fmac_f32_dpp v2, v32, v19 row_newbcast:15 row_mask:0xf bank_mask:0xf bound_ctrl:1
	v_mul_f32_dpp v24, v33, v17 row_newbcast:0 row_mask:0xf bank_mask:0xf bound_ctrl:1
	v_mul_f32_dpp v23, v33, v16 row_newbcast:1 row_mask:0xf bank_mask:0xf bound_ctrl:1
	v_mul_f32_dpp v25, v33, v15 row_newbcast:2 row_mask:0xf bank_mask:0xf bound_ctrl:1
	v_mul_f32_dpp v26, v33, v14 row_newbcast:3 row_mask:0xf bank_mask:0xf bound_ctrl:1
	v_fmac_f32_dpp v24, v33, v13 row_newbcast:4 row_mask:0xf bank_mask:0xf bound_ctrl:1
	v_fmac_f32_dpp v23, v33, v12 row_newbcast:5 row_mask:0xf bank_mask:0xf bound_ctrl:1
	v_fmac_f32_dpp v25, v33, v11 row_newbcast:6 row_mask:0xf bank_mask:0xf bound_ctrl:1
	v_fmac_f32_dpp v26, v33, v10 row_newbcast:7 row_mask:0xf bank_mask:0xf bound_ctrl:1
	s_nop 0
	v_fmac_f32_dpp v24, v33, v9 row_newbcast:8 row_mask:0xf bank_mask:0xf bound_ctrl:1
	v_fmac_f32_dpp v23, v33, v8 row_newbcast:9 row_mask:0xf bank_mask:0xf bound_ctrl:1
	v_fmac_f32_dpp v25, v33, v7 row_newbcast:10 row_mask:0xf bank_mask:0xf bound_ctrl:1
	v_fmac_f32_dpp v26, v33, v6 row_newbcast:11 row_mask:0xf bank_mask:0xf bound_ctrl:1
	s_nop 0
	v_fmac_f32_dpp v24, v33, v5 row_newbcast:12 row_mask:0xf bank_mask:0xf bound_ctrl:1
	v_fmac_f32_dpp v23, v33, v4 row_newbcast:13 row_mask:0xf bank_mask:0xf bound_ctrl:1
	v_fmac_f32_dpp v25, v33, v3 row_newbcast:14 row_mask:0xf bank_mask:0xf bound_ctrl:1
	v_fmac_f32_dpp v26, v33, v2 row_newbcast:15 row_mask:0xf bank_mask:0xf bound_ctrl:1
	v_mov_b32_e32 v18, v224
	ds_read_b32 v21, v21 offset:3840
	s_waitcnt lgkmcnt(0)
	v_mul_f32_dpp v17, v21, v17 row_newbcast:0 row_mask:0xf bank_mask:0xf bound_ctrl:1
	v_mul_f32_dpp v16, v21, v16 row_newbcast:1 row_mask:0xf bank_mask:0xf bound_ctrl:1
	v_mul_f32_dpp v15, v21, v15 row_newbcast:2 row_mask:0xf bank_mask:0xf bound_ctrl:1
	v_mul_f32_dpp v14, v21, v14 row_newbcast:3 row_mask:0xf bank_mask:0xf bound_ctrl:1
	v_mul_f32_dpp v13, v21, v13 row_newbcast:4 row_mask:0xf bank_mask:0xf bound_ctrl:1
	v_mul_f32_dpp v12, v21, v12 row_newbcast:5 row_mask:0xf bank_mask:0xf bound_ctrl:1
	v_mul_f32_dpp v11, v21, v11 row_newbcast:6 row_mask:0xf bank_mask:0xf bound_ctrl:1
	v_mul_f32_dpp v10, v21, v10 row_newbcast:7 row_mask:0xf bank_mask:0xf bound_ctrl:1
	v_mul_f32_dpp v9, v21, v9 row_newbcast:8 row_mask:0xf bank_mask:0xf bound_ctrl:1
	v_mul_f32_dpp v8, v21, v8 row_newbcast:9 row_mask:0xf bank_mask:0xf bound_ctrl:1
	v_mul_f32_dpp v7, v21, v7 row_newbcast:10 row_mask:0xf bank_mask:0xf bound_ctrl:1
	v_mul_f32_dpp v6, v21, v6 row_newbcast:11 row_mask:0xf bank_mask:0xf bound_ctrl:1
	v_mul_f32_dpp v5, v21, v5 row_newbcast:12 row_mask:0xf bank_mask:0xf bound_ctrl:1
	v_mul_f32_dpp v4, v21, v4 row_newbcast:13 row_mask:0xf bank_mask:0xf bound_ctrl:1
	v_mul_f32_dpp v3, v21, v3 row_newbcast:14 row_mask:0xf bank_mask:0xf bound_ctrl:1
	v_mul_f32_dpp v2, v21, v2 row_newbcast:15 row_mask:0xf bank_mask:0xf bound_ctrl:1
	v_add_f32 v24, v24, v23
	v_add_f32 v25, v25, v26
	ds_write_b64 v20, v[24:25] offset:30720
	s_waitcnt lgkmcnt(0)
	s_barrier
	s_cbranch_scc1 .LBB0_583
